# rwkv scans: LDS XOR swizzle makes MFMA fragment ds_read_b128 bank-conflict free; ds_reads hoisted per barrier segment; chunk loads prefetched
# speedup vs baseline: 1.0533x; 1.0332x over previous
; __device__ __forceinline__ unsigned f2bf(float f) { return pk2(f, 0.f) & 0xffffu; }
; template <bool PA> ...
;     bf16* M = (bf16*)lds;
;     ...
;     bf16* w2T = MAT(13); bf16* a2T = MAT(14); float* wc = (float*)MAT(15); float* cst = wc + 64;
;     float* zbuf = (float*)MAT(0); float* abuf = zbuf + 4096;
;     float* cumb = (float*)MAT(10); float* segtot = cumb + 4096;
;     const int nch = slab == 0 ? 129 : 257, G = slab == 0 ? 4 : 8, nitems = 256, NCHA = nch;
;     const int lane = tid & 63, wave = tid >> 6, r16 = lane & 15, kq = lane >> 4, mt = wave >> 1, ntb = 2 * (wave & 1);
;     const int j = tid >> 3, part = tid & 7, c8 = part * 8;
;     const int tunit = ((j >> 3) + 1) * (4 * (j >> 3) + (j & 7)) + part; const bool tlow = part <= (j >> 3);
;     for (int item = blockIdx.x; item < nitems; item += gridDim.x) {
;         const int g = item % G, strm = item / G; const int p0 = g == 0 ? 0 : 1 + 32 * g, p1 = 33 + 32 * g;
;         const bool haveT = !PA;
;         const int d = strm & 1, head = (strm >> 1) & 15, sq = strm >> 5; const int seqbase = sq * 8256; const int hc8 = head * 64 + c8;
;         bf16* Op = d ? OBb : OFb;
;         const float* w0 = a->in[15] + d * 1024; const float* w2 = a->in[17] + (size_t)d * 64 * 1024; const float* a0 = a->in[18] + d * 1024; const float* a2 = a->in[20] + (size_t)d * 64 * 1024;
;         __syncthreads();
;         if (tid < 320) { const int wch = tid >> 6, cc = tid & 63; const float* src = wch == 0 ? w0 : (wch == 1 ? a0 : (wch == 2 ? a->in[23] : (wch == 3 ? a->in[24] : a->in[25]))); cst[tid] = src[head * 64 + cc]; }
;         for (int i = tid; i < 4096; i += 512) { const int l = i >> 6, cc = i & 63; w2T[cc * 72 + l] = (bf16)f2bf(w2[(size_t)l * 1024 + head * 64 + cc]); a2T[cc * 72 + l] = (bf16)f2bf(a2[(size_t)l * 1024 + head * 64 + cc]); }
;         f32x4_t Sacc[2], S2acc[2]; Sacc[0] = (f32x4_t){0.f, 0.f, 0.f, 0.f}; Sacc[1] = Sacc[0];
; #pragma unroll
;         for (int i = 0; i < 2; ++i)
; #pragma unroll
;             for (int e = 0; e < 4; ++e) S2acc[i][e] = (16 * mt + 4 * kq + e == 16 * (ntb + i) + r16) ? 1.f : 0.f;
.LBB0_123:
	s_and_b64 vcc, exec, s[0:1]
	s_cbranch_vccz .LBB0_388
	s_cmp_lt_i32 s65, 9
	s_mov_b64 s[0:1], -1
	s_cbranch_scc1 .LBB0_251
	s_cmp_gt_i32 s65, 9
	s_cbranch_scc0 .LBB0_190
	v_readlane_b32 s0, v253, 2
	v_writelane_b32 v255, s70, 18
	v_readlane_b32 s1, v253, 3
	s_mov_b32 s39, s40
	v_writelane_b32 v255, s71, 19
	s_andn2_b64 vcc, exec, s[0:1]
	s_cbranch_vccnz .LBB0_189
	s_add_u32 s0, s6, 0x9a00000
	s_addc_u32 s1, s7, 0
	v_writelane_b32 v255, s0, 30
	v_ashrrev_i32_e32 v83, 6, v202
	v_ashrrev_i32_e32 v84, 3, v202
	v_writelane_b32 v255, s1, 31
	s_add_u32 s0, s6, 0xba80000
	s_addc_u32 s1, s7, 0
	v_writelane_b32 v255, s0, 34
	v_lshlrev_b32_e32 v0, 1, v83
	v_and_b32_e32 v9, 2, v0
	v_writelane_b32 v255, s1, 35
	s_add_u32 s0, s6, 0xdb00000
	s_addc_u32 s1, s7, 0
	v_writelane_b32 v255, s0, 28
	v_and_b32_e32 v0, 7, v84
	v_lshl_add_u32 v0, v83, 2, v0
	v_writelane_b32 v255, s1, 29
	s_add_u32 s0, s6, 0x100000
	v_writelane_b32 v255, s0, 14
	s_addc_u32 s0, s7, 0
	v_writelane_b32 v255, s0, 15
	s_cmp_eq_u32 s39, 0
	s_movk_i32 s0, 0x81
	s_cselect_b32 s91, s0, 0x101
	v_mad_u64_u32 v[2:3], s[0:1], v0, v83, v[0:1]
	v_readlane_b32 s0, v255, 5
	v_readlane_b32 s1, v255, 6
	s_load_dwordx2 s[10:11], s[0:1], 0x78
	s_load_dwordx4 s[20:23], s[0:1], 0x88
	s_load_dwordx2 s[42:43], s[0:1], 0xa0
	s_movk_i32 s0, 0x140
	v_cmp_gt_i32_e64 s[0:1], s0, v202
	s_waitcnt lgkmcnt(0)
	v_writelane_b32 v255, s10, 10
	v_and_b32_e32 v10, 15, v203
	v_bfe_u32 v11, v203, 4, 2
	v_writelane_b32 v255, s11, 11
	v_writelane_b32 v255, s20, 22
	v_and_b32_e32 v13, -16, v84
	v_lshl_or_b32 v14, v11, 2, v13
	v_writelane_b32 v255, s21, 23
	v_writelane_b32 v255, s22, 24
	v_writelane_b32 v255, s23, 25
	v_writelane_b32 v255, s0, 32
	v_lshlrev_b32_e32 v3, 1, v10
	v_add_u32_e32 v0, 0, v3
	v_writelane_b32 v255, s1, 33
	v_cmp_lt_u32_e64 s[0:1], 63, v202
	v_lshlrev_b32_e32 v17, 5, v9
	v_lshl_or_b32 v22, v9, 4, v10
	v_writelane_b32 v255, s0, 12
	v_and_b32_e32 v8, 7, v203
	v_and_b32_e32 v20, 48, v203
	v_writelane_b32 v255, s1, 13
	s_movk_i32 s0, 0x1000
	v_cmp_gt_i32_e64 s[10:11], s0, v202
	s_cselect_b32 s0, 2, 3
	v_and_b32_e32 v82, 63, v203
	v_writelane_b32 v255, s10, 20
	s_mov_b64 s[12:13], 0x730000
	v_lshlrev_b32_e32 v12, 2, v202
	v_writelane_b32 v255, s11, 21
	v_writelane_b32 v255, s0, 26
	s_movk_i32 s0, 0x90
	v_mul_lo_u32 v16, v14, s0
	v_add3_u32 v87, v0, v16, v17
	v_bfi_b32 v0, -16, v84, v203
	v_mul_lo_u32 v18, v0, s0
	v_mul_u32_u24_e32 v0, 0x48, v22
	v_lshlrev_b32_e32 v23, 1, v0
	v_lshlrev_b32_e32 v0, 4, v8
	s_waitcnt vmcnt(0)
	v_mul_lo_u32 v30, v84, s0
	v_readlane_b32 s0, v254, 31
	v_lshl_add_u64 v[6:7], s[6:7], 0, v[0:1]
	v_lshlrev_b32_e32 v25, 2, v82
	v_add3_u32 v93, s0, v20, v23
	v_readlane_b32 s0, v254, 32
	v_lshl_add_u64 v[42:43], v[6:7], 0, s[12:13]
	s_mov_b64 s[12:13], 0xb40000
	v_add3_u32 v94, s0, v20, v23
	v_readlane_b32 s0, v254, 33
	v_add_u32_e32 v24, 0, v0
	v_lshl_add_u64 v[44:45], v[6:7], 0, s[12:13]
	v_lshlrev_b32_e32 v6, 8, v84
	v_add_u32_e32 v98, s0, v12
	v_add_u32_e32 v99, s0, v25
	v_readlane_b32 s0, v254, 28
	v_add_u32_e32 v21, 0, v20
	v_readlane_b32 s2, v254, 27
	v_add3_u32 v95, v24, v0, v6
	v_lshlrev_b32_e32 v7, 5, v8
	v_add3_u32 v101, s0, v0, v30
	v_add_u32_e32 v0, 0x900, v23
	v_add3_u32 v97, s2, v7, v6
	v_add_u32_e32 v6, v21, v0
	v_readlane_b32 s1, v254, 26
	v_lshlrev_b32_e32 v19, 3, v11
	v_add_u32_e32 v105, 0xfc00, v6
	v_add_u32_e32 v106, 0xfc40, v6
	v_lshlrev_b32_e32 v6, 1, v13
	s_cselect_b32 s8, 4, 8
	v_add_u32_e32 v86, s1, v12
	v_add_u32_e32 v26, s2, v25
	v_add_u32_e32 v27, s2, v3
	v_readlane_b32 s9, v254, 29
	v_readlane_b32 s10, v254, 30
	v_add3_u32 v107, s2, v18, v20
	v_add3_u32 v12, 0, v6, v19
	s_mov_b32 s2, 0xfc00
	v_add3_u32 v110, s0, v18, v20
	s_add_i32 s0, 0, 0x12000
	v_add_u32_e32 v28, s9, v3
	v_add_u32_e32 v29, s10, v3
	v_add3_u32 v109, v12, v0, s2
	v_add_u32_e32 v0, s0, v6
	v_lshlrev_b32_e32 v85, 3, v8
	v_cmp_le_i32_e64 s[36:37], v8, v83
	v_add_lshl_u32 v2, v2, v8, 3
	v_add_u32_e32 v96, s1, v7
	v_cmp_eq_u32_e64 s[44:45], 0, v8
	v_readlane_b32 s1, v254, 34
	v_add3_u32 v102, v27, v16, v17
	v_add3_u32 v103, v28, v16, v17
	v_add3_u32 v104, v29, v16, v17
	v_add3_u32 v111, v0, v19, v23
	v_add_u32_e32 v0, s0, v20
	v_or_b32_e32 v16, 1, v9
	v_mul_u32_u24_e32 v8, 0x240, v8
	v_lshlrev_b32_e32 v15, 1, v84
	v_add_u32_e32 v113, v0, v23
	v_add_u32_e32 v115, v0, v18
	v_lshl_add_u32 v0, v10, 2, s1
	v_or_b32_e32 v6, 1, v14
	v_lshl_or_b32 v10, v16, 4, v10
	v_lshlrev_b32_e32 v8, 1, v8
	v_add3_u32 v117, 0, v15, v8
	v_add3_u32 v118, 0, v8, v15
	v_lshlrev_b32_e32 v15, 6, v6
	v_cmp_gt_i32_e64 s[78:79], v22, v6
	v_cmp_gt_i32_e64 s[84:85], v10, v6
	v_cvt_f32_ubyte0_e32 v6, s8
	v_rcp_iflag_f32_e32 v6, v6
	v_lshlrev_b32_e32 v4, 6, v84
	v_ashrrev_i32_e32 v5, 31, v4
	v_lshlrev_b64 v[46:47], 2, v[4:5]
	v_mul_f32_e32 v6, 0x4f7ffffe, v6
	v_cvt_u32_f32_e32 v6, v6
	v_and_b32_e32 v4, 0xfffffc00, v4
	v_lshlrev_b32_e32 v5, 8, v11
	v_add_u32_e32 v108, v12, v23
	v_or_b32_e32 v12, 2, v14
	v_or_b32_e32 v13, 3, v14
	v_or3_b32 v4, v4, v5, v22
	v_add_u32_e32 v89, v21, v23
	v_add_u32_e32 v92, v21, v18
	v_add_u32_e32 v100, s1, v7
	v_lshlrev_b32_e32 v17, 6, v14
	v_lshlrev_b32_e32 v19, 6, v12
	v_lshlrev_b32_e32 v21, 6, v13
	v_readfirstlane_b32 s1, v6
	v_or_b32_e32 v6, 64, v4
	v_add3_u32 v88, 0, v18, v20
	v_add3_u32 v112, s9, v18, v20
	v_add3_u32 v114, s10, v18, v20
	v_or_b32_e32 v18, v10, v17
	v_or_b32_e32 v8, v22, v17
	v_or_b32_e32 v17, v15, v22
	v_or_b32_e32 v20, v19, v22
	v_or_b32_e32 v23, v21, v22
	v_or_b32_e32 v15, v10, v15
	v_or_b32_e32 v19, v10, v19
	v_or_b32_e32 v21, v10, v21
	v_cmp_lt_i32_e64 s[70:71], v10, v14
	v_cmp_gt_i32_e64 s[72:73], v10, v14
	v_cmp_lt_i32_e64 s[74:75], v10, v12
; template <bool PA> ...
;     ...
;     bf16* w2T = MAT(13); bf16* a2T = MAT(14); float* wc = (float*)MAT(15); float* cst = wc + 64;
;     float* zbuf = (float*)MAT(0); float* abuf = zbuf + 4096;
;     float* cumb = (float*)MAT(10); float* segtot = cumb + 4096;
;     const int nch = slab == 0 ? 129 : 257, G = slab == 0 ? 4 : 8, nitems = 256, NCHA = nch;
;     const int lane = tid & 63, wave = tid >> 6, r16 = lane & 15, kq = lane >> 4, mt = wave >> 1, ntb = 2 * (wave & 1);
;     const int j = tid >> 3, part = tid & 7, c8 = part * 8;
;     const int tunit = ((j >> 3) + 1) * (4 * (j >> 3) + (j & 7)) + part; const bool tlow = part <= (j >> 3);
	v_cmp_lt_i32_e64 s[76:77], v10, v13
	v_cmp_gt_i32_e64 s[86:87], v10, v12
	v_cmp_gt_i32_e64 s[88:89], v10, v13
	v_or_b32_e32 v46, v46, v7
	v_mov_b64_e32 v[10:11], 0x1800000
	v_ashrrev_i32_e32 v7, 31, v6
	v_lshl_add_u64 v[50:51], v[6:7], 2, v[10:11]
	v_or_b32_e32 v6, 0x80, v4
	v_ashrrev_i32_e32 v7, 31, v6
	v_lshl_add_u64 v[52:53], v[6:7], 2, v[10:11]
	v_or_b32_e32 v6, 0xc0, v4
	v_ashrrev_i32_e32 v7, 31, v6
	v_lshl_add_u64 v[54:55], v[6:7], 2, v[10:11]
	v_or_b32_e32 v6, 16, v4
	s_sub_i32 s0, 0, s8
	v_ashrrev_i32_e32 v7, 31, v6
	s_mul_i32 s0, s0, s1
	v_lshl_add_u64 v[56:57], v[6:7], 2, v[10:11]
	v_or_b32_e32 v6, 0x50, v4
	v_ashrrev_i32_e32 v3, 31, v2
	s_mul_hi_u32 s0, s1, s0
	v_ashrrev_i32_e32 v5, 31, v4
	v_ashrrev_i32_e32 v7, 31, v6
	s_add_i32 s10, s1, s0
	v_lshl_add_u64 v[48:49], v[4:5], 2, v[10:11]
	v_lshl_add_u64 v[58:59], v[6:7], 2, v[10:11]
	v_or_b32_e32 v6, 0x90, v4
	v_or_b32_e32 v4, 0xd0, v4
	v_lshl_add_u64 v[2:3], v[2:3], 1, s[6:7]
	s_mov_b64 s[0:1], 0x2000000
	v_add_u32_e32 v91, v24, v30
	v_lshlrev_b32_e32 v24, 11, v83
	v_lshl_add_u32 v119, v8, 2, 0
	v_lshlrev_b32_e32 v8, 6, v9
	v_lshlrev_b32_e32 v9, 6, v16
	v_ashrrev_i32_e32 v7, 31, v6
	v_ashrrev_i32_e32 v5, 31, v4
	v_lshl_add_u64 v[64:65], v[2:3], 0, s[0:1]
	s_add_i32 s0, s91, -1
	v_sub_u32_e32 v90, 63, v84
	v_cmp_eq_u32_e64 s[46:47], 63, v84
	v_mul_u32_u24_e32 v116, 0x48, v82
	v_lshl_add_u32 v120, v17, 2, 0
	v_lshl_add_u32 v121, v20, 2, 0
	v_lshl_add_u32 v122, v23, 2, 0
	v_lshl_add_u32 v123, v18, 2, 0
	v_lshl_add_u32 v124, v15, 2, 0
	v_lshl_add_u32 v125, v19, 2, 0
	v_lshl_add_u32 v126, v21, 2, 0
	v_cmp_lt_i32_e64 s[48:49], 0, v83
	v_cmp_lt_i32_e64 s[50:51], 1, v83
	v_cmp_lt_i32_e64 s[52:53], 2, v83
	v_cmp_lt_i32_e64 s[54:55], 3, v83
	v_cmp_lt_i32_e64 s[56:57], 4, v83
	v_cmp_lt_i32_e64 s[58:59], 5, v83
	v_cmp_lt_i32_e64 s[60:61], 6, v83
	v_cmp_lt_i32_e64 s[62:63], v22, v14
	v_cmp_gt_i32_e64 s[64:65], v22, v14
	v_cmp_lt_i32_e64 s[66:67], v22, v12
	v_cmp_lt_i32_e64 s[68:69], v22, v13
	v_cmp_gt_i32_e64 s[80:81], v22, v12
	v_cmp_gt_i32_e64 s[82:83], v22, v13
	v_lshl_add_u64 v[60:61], v[6:7], 2, v[10:11]
	v_lshl_add_u64 v[62:63], v[4:5], 2, v[10:11]
	v_writelane_b32 v255, s0, 16
	v_add_u32_e32 v127, v0, v8
	v_add_u32_e32 v128, v0, v9
	v_add_u32_e32 v129, v26, v24
	v_readfirstlane_b32 s9, v202
	v_mov_b32_e32 v176, v117
	s_mov_b32 s0, 0xff0000
	s_mov_b32 s1, 0xff
	v_cndmask_b32_e64 v201, 0, 16, s[0:1]
	s_mov_b32 s0, 0xff000000
	s_mov_b32 s1, 0xff00
	v_cndmask_b32_e64 v252, 0, 16, s[0:1]
	v_sub_u32_e32 v201, v201, v252
	v_add_u32_e32 v87, v87, v201
	s_mov_b32 s0, 0xff0
	s_mov_b32 s1, 0xff0
	v_cndmask_b32_e64 v201, 0, 16, s[0:1]
	s_mov_b32 s0, 0xff00000
	s_mov_b32 s1, 0xff00000
	v_cndmask_b32_e64 v252, 0, 16, s[0:1]
	v_sub_u32_e32 v201, v201, v252
	v_add_u32_e32 v88, v88, v201
	s_mov_b32 s0, 0xff0
	s_mov_b32 s1, 0xff0
	v_cndmask_b32_e64 v201, 0, 16, s[0:1]
	s_mov_b32 s0, 0xff00000
	s_mov_b32 s1, 0xff00000
	v_cndmask_b32_e64 v252, 0, 16, s[0:1]
	v_sub_u32_e32 v201, v201, v252
	v_add_u32_e32 v89, v89, v201
	s_mov_b32 s0, 0x0
	s_mov_b32 s1, 0x55555555
	s_bitcmp1_b32 s9, 6
	s_cmov_b32 s0, 0x55555555
	s_cmov_b32 s1, 0x0
	v_cndmask_b32_e64 v201, 0, 16, s[0:1]
	s_mov_b32 s0, 0x0
	s_mov_b32 s1, 0xaaaaaaaa
	s_bitcmp1_b32 s9, 6
	s_cmov_b32 s0, 0xaaaaaaaa
	s_cmov_b32 s1, 0x0
	v_cndmask_b32_e64 v252, 0, 16, s[0:1]
	v_sub_u32_e32 v201, v201, v252
	v_add_u32_e32 v91, v91, v201
	s_mov_b32 s0, 0xff0
	s_mov_b32 s1, 0xff0
	v_cndmask_b32_e64 v201, 0, 16, s[0:1]
	s_mov_b32 s0, 0xff00000
	s_mov_b32 s1, 0xff00000
	v_cndmask_b32_e64 v252, 0, 16, s[0:1]
	v_sub_u32_e32 v201, v201, v252
	v_add_u32_e32 v92, v92, v201
	s_mov_b32 s0, 0x0
	s_mov_b32 s1, 0x55555555
	s_bitcmp1_b32 s9, 6
	s_cmov_b32 s0, 0x55555555
	s_cmov_b32 s1, 0x0
	v_cndmask_b32_e64 v201, 0, 16, s[0:1]
	s_mov_b32 s0, 0x0
	s_mov_b32 s1, 0xaaaaaaaa
	s_bitcmp1_b32 s9, 6
	s_cmov_b32 s0, 0xaaaaaaaa
	s_cmov_b32 s1, 0x0
	v_cndmask_b32_e64 v252, 0, 16, s[0:1]
	v_sub_u32_e32 v201, v201, v252
	v_add_u32_e32 v101, v101, v201
	s_mov_b32 s0, 0xff0000
	s_mov_b32 s1, 0xff
	v_cndmask_b32_e64 v201, 0, 16, s[0:1]
	s_mov_b32 s0, 0xff000000
	s_mov_b32 s1, 0xff00
	v_cndmask_b32_e64 v252, 0, 16, s[0:1]
	v_sub_u32_e32 v201, v201, v252
; template <bool PA> ...
;     ...
;     bf16* w2T = MAT(13); bf16* a2T = MAT(14); float* wc = (float*)MAT(15); float* cst = wc + 64;
;     float* zbuf = (float*)MAT(0); float* abuf = zbuf + 4096;
;     float* cumb = (float*)MAT(10); float* segtot = cumb + 4096;
;     const int nch = slab == 0 ? 129 : 257, G = slab == 0 ? 4 : 8, nitems = 256, NCHA = nch;
;     const int lane = tid & 63, wave = tid >> 6, r16 = lane & 15, kq = lane >> 4, mt = wave >> 1, ntb = 2 * (wave & 1);
;     const int j = tid >> 3, part = tid & 7, c8 = part * 8;
;     const int tunit = ((j >> 3) + 1) * (4 * (j >> 3) + (j & 7)) + part; const bool tlow = part <= (j >> 3);
	v_add_u32_e32 v102, v102, v201
	s_mov_b32 s0, 0xff0000
	s_mov_b32 s1, 0xff
	v_cndmask_b32_e64 v201, 0, 16, s[0:1]
	s_mov_b32 s0, 0xff000000
	s_mov_b32 s1, 0xff00
	v_cndmask_b32_e64 v252, 0, 16, s[0:1]
	v_sub_u32_e32 v201, v201, v252
	v_add_u32_e32 v103, v103, v201
	s_mov_b32 s0, 0xff0000
	s_mov_b32 s1, 0xff
	v_cndmask_b32_e64 v201, 0, 16, s[0:1]
	s_mov_b32 s0, 0xff000000
	s_mov_b32 s1, 0xff00
	v_cndmask_b32_e64 v252, 0, 16, s[0:1]
	v_sub_u32_e32 v201, v201, v252
	v_add_u32_e32 v104, v104, v201
	s_mov_b32 s0, 0xff0
	s_mov_b32 s1, 0xff0
	v_cndmask_b32_e64 v201, 0, 16, s[0:1]
	s_mov_b32 s0, 0xff00000
	s_mov_b32 s1, 0xff00000
	v_cndmask_b32_e64 v252, 0, 16, s[0:1]
	v_sub_u32_e32 v201, v201, v252
	v_add_u32_e32 v105, v105, v201
	s_mov_b32 s0, 0xff0
	s_mov_b32 s1, 0xff0
	v_cndmask_b32_e64 v201, 0, 16, s[0:1]
	s_mov_b32 s0, 0xff00000
	s_mov_b32 s1, 0xff00000
	v_cndmask_b32_e64 v252, 0, 16, s[0:1]
	v_sub_u32_e32 v201, v201, v252
	v_add_u32_e32 v106, v106, v201
	s_mov_b32 s0, 0xff0
	s_mov_b32 s1, 0xff0
	v_cndmask_b32_e64 v201, 0, 16, s[0:1]
	s_mov_b32 s0, 0xff00000
	s_mov_b32 s1, 0xff00000
	v_cndmask_b32_e64 v252, 0, 16, s[0:1]
	v_sub_u32_e32 v201, v201, v252
	v_add_u32_e32 v107, v107, v201
	s_mov_b32 s0, 0xff00ff0
	s_mov_b32 s1, 0x0
	v_cndmask_b32_e64 v201, 0, 16, s[0:1]
	s_mov_b32 s0, 0x0
	s_mov_b32 s1, 0xff00ff0
	v_cndmask_b32_e64 v252, 0, 16, s[0:1]
	v_sub_u32_e32 v201, v201, v252
	v_add_u32_e32 v108, v108, v201
	s_mov_b32 s0, 0xff00ff0
	s_mov_b32 s1, 0x0
	v_cndmask_b32_e64 v201, 0, 16, s[0:1]
	s_mov_b32 s0, 0x0
	s_mov_b32 s1, 0xff00ff0
	v_cndmask_b32_e64 v252, 0, 16, s[0:1]
	v_sub_u32_e32 v201, v201, v252
	v_add_u32_e32 v109, v109, v201
	s_mov_b32 s0, 0xff0
	s_mov_b32 s1, 0xff0
	v_cndmask_b32_e64 v201, 0, 16, s[0:1]
	s_mov_b32 s0, 0xff00000
	s_mov_b32 s1, 0xff00000
	v_cndmask_b32_e64 v252, 0, 16, s[0:1]
	v_sub_u32_e32 v201, v201, v252
	v_add_u32_e32 v110, v110, v201
	s_mov_b32 s0, 0xff00ff0
	s_mov_b32 s1, 0x0
	v_cndmask_b32_e64 v201, 0, 16, s[0:1]
	s_mov_b32 s0, 0x0
	s_mov_b32 s1, 0xff00ff0
	v_cndmask_b32_e64 v252, 0, 16, s[0:1]
	v_sub_u32_e32 v201, v201, v252
	v_add_u32_e32 v111, v111, v201
	s_mov_b32 s0, 0xff0
	s_mov_b32 s1, 0xff0
	v_cndmask_b32_e64 v201, 0, 16, s[0:1]
	s_mov_b32 s0, 0xff00000
	s_mov_b32 s1, 0xff00000
	v_cndmask_b32_e64 v252, 0, 16, s[0:1]
	v_sub_u32_e32 v201, v201, v252
	v_add_u32_e32 v112, v112, v201
	s_mov_b32 s0, 0xff0
	s_mov_b32 s1, 0xff0
	v_cndmask_b32_e64 v201, 0, 16, s[0:1]
	s_mov_b32 s0, 0xff00000
	s_mov_b32 s1, 0xff00000
	v_cndmask_b32_e64 v252, 0, 16, s[0:1]
	v_sub_u32_e32 v201, v201, v252
	v_add_u32_e32 v113, v113, v201
	s_mov_b32 s0, 0xff0
	s_mov_b32 s1, 0xff0
	v_cndmask_b32_e64 v201, 0, 16, s[0:1]
	s_mov_b32 s0, 0xff00000
	s_mov_b32 s1, 0xff00000
	v_cndmask_b32_e64 v252, 0, 16, s[0:1]
	v_sub_u32_e32 v201, v201, v252
	v_add_u32_e32 v114, v114, v201
	s_mov_b32 s0, 0xff0
	s_mov_b32 s1, 0xff0
	v_cndmask_b32_e64 v201, 0, 16, s[0:1]
	s_mov_b32 s0, 0xff00000
	s_mov_b32 s1, 0xff00000
	v_cndmask_b32_e64 v252, 0, 16, s[0:1]
	v_sub_u32_e32 v201, v201, v252
	v_add_u32_e32 v115, v115, v201
	s_mov_b32 s0, 0xaaaaaaaa
	s_mov_b32 s1, 0xaaaaaaaa
	s_bitcmp1_b32 s9, 6
	s_cmov_b32 s0, 0x0
	s_cmov_b32 s1, 0x0
	v_cndmask_b32_e64 v201, 0, 16, s[0:1]
	s_mov_b32 s0, 0x0
	s_mov_b32 s1, 0x0
	s_bitcmp1_b32 s9, 6
	s_cmov_b32 s0, 0xaaaaaaaa
	s_cmov_b32 s1, 0xaaaaaaaa
	v_cndmask_b32_e64 v252, 0, 16, s[0:1]
	v_sub_u32_e32 v201, v201, v252
	v_add_u32_e32 v117, v117, v201
	s_mov_b32 s0, 0x55555555
	s_mov_b32 s1, 0x55555555
	s_bitcmp1_b32 s9, 6
	s_cmov_b32 s0, 0x0
	s_cmov_b32 s1, 0x0
	v_cndmask_b32_e64 v201, 0, 16, s[0:1]
	s_mov_b32 s0, 0x0
	s_mov_b32 s1, 0x0
	s_bitcmp1_b32 s9, 6
	s_cmov_b32 s0, 0x55555555
	s_cmov_b32 s1, 0x55555555
	v_cndmask_b32_e64 v252, 0, 16, s[0:1]
	v_sub_u32_e32 v201, v201, v252
	v_add_u32_e32 v176, v176, v201
	s_mov_b32 s0, 0x55555555
	s_mov_b32 s1, 0x55555555
	s_bitcmp1_b32 s9, 6
	s_cmov_b32 s0, 0x0
	s_cmov_b32 s1, 0x0
	v_cndmask_b32_e64 v201, 0, 16, s[0:1]
	s_mov_b32 s0, 0x0
	s_mov_b32 s1, 0x0
	s_bitcmp1_b32 s9, 6
	s_cmov_b32 s0, 0x55555555
	s_cmov_b32 s1, 0x55555555
	v_cndmask_b32_e64 v252, 0, 16, s[0:1]
	v_sub_u32_e32 v201, v201, v252
	v_add_u32_e32 v118, v118, v201
	s_mov_b32 s2, s96
	s_branch .LBB0_129

; __device__ __forceinline__ unsigned pk2(float lo, float hi) { const f32x2_cv v = {lo, hi}; const bf16x2_cv b = __builtin_convertvector(v, bf16x2_cv); return __builtin_bit_cast(unsigned, b); }
; template <bool PA> ...
;     ...
;             {
;                 const f32x4_t c0 = *(const f32x4_t*)(cumb + j * 64 + c8), c1 = *(const f32x4_t*)(cumb + j * 64 + c8 + 4);
;                 float ah[8], bh[8], kh[8], rh[8];
; #pragma unroll
;                 for (int e = 0; e < 8; ++e) { const float cu = e < 4 ? c0[e & 3] : c1[e & 3]; const float Wt = __expf(cu), iW = __expf(-cu), Wm1 = __expf(cu - lw[e]);
;                     ah[e] = kk[e] * Wm1; bh[e] = -(kk[e] * av[e]) * iW; kh[e] = kd[e] * iW; rh[e] = rv[e] * Wt;
;                     if (j == 63) wc[c8 + e] = Wt; }
;                 u32x4_t w;
;                 w.x = pk2(ah[0], ah[1]); w.y = pk2(ah[2], ah[3]); w.z = pk2(ah[4], ah[5]); w.w = pk2(ah[6], ah[7]); *(u32x4_t*)(MAT(0) + j * 72 + c8) = w;
;                 u32x4_t wb, wk;
;                 wb.x = pk2(bh[0], bh[1]); wb.y = pk2(bh[2], bh[3]); wb.z = pk2(bh[4], bh[5]); wb.w = pk2(bh[6], bh[7]); *(u32x4_t*)(MAT(1) + j * 72 + c8) = wb;
;                 wk.x = pk2(kh[0], kh[1]); wk.y = pk2(kh[2], kh[3]); wk.z = pk2(kh[4], kh[5]); wk.w = pk2(kh[6], kh[7]); *(u32x4_t*)(MAT(2) + j * 72 + c8) = wk;
;                 w.x = pk2(rh[0], rh[1]); w.y = pk2(rh[2], rh[3]); w.z = pk2(rh[4], rh[5]); w.w = pk2(rh[6], rh[7]); *(u32x4_t*)(MAT(3) + j * 72 + c8) = w;
;                 { const unsigned wba[4] = {wb.x, wb.y, wb.z, wb.w}, wka[4] = {wk.x, wk.y, wk.z, wk.w}, wva[4] = {vraw.x, vraw.y, vraw.z, vraw.w};
; #pragma unroll
;                   for (int q = 0; q < 4; ++q) { bf16* d4 = MAT(4) + (c8 + 2 * q) * 72 + j; bf16* d5 = MAT(5) + (c8 + 2 * q) * 72 + j; bf16* d6 = MAT(6) + (c8 + 2 * q) * 72 + j;
;                       d4[0] = (bf16)(wba[q] & 0xffffu); d4[72] = (bf16)(wba[q] >> 16); d5[0] = (bf16)(wka[q] & 0xffffu); d5[72] = (bf16)(wka[q] >> 16); d6[0] = (bf16)(wva[q] & 0xffffu); d6[72] = (bf16)(wva[q] >> 16); } }
;                 if (haveT) *(u32x4_t*)(MAT(9) + j * 72 + c8) = tld;
;                 st_rm(MAT(7), Sacc, mt, ntb, r16, kq);
;                 if (PA) st_rm(MAT(12), S2acc, mt, ntb, r16, kq);
.LBB0_152:
	s_or_b64 exec, exec, s[0:1]
	v_lshlrev_b64 v[34:35], 10, v[80:81]
	v_add_f32_e32 v80, v149, v150
	v_max_f32_e32 v80, 0x179abe15, v80
	v_sub_f32_e32 v25, v33, v25
	v_rsq_f32_e32 v80, v80
	v_mul_f32_e32 v25, 0x3fb8aa3b, v25
	v_sub_f32_e32 v24, v32, v24
	v_exp_f32_e32 v25, v25
	v_mul_f32_e32 v24, 0x3fb8aa3b, v24
	v_sub_f32_e32 v23, v31, v23
	v_exp_f32_e32 v24, v24
	v_mul_f32_e32 v23, 0x3fb8aa3b, v23
	v_exp_f32_e32 v23, v23
	v_mul_f32_e32 v81, v145, v80
	v_mul_f32_e32 v145, 0xbfb8aa3b, v33
	v_mul_f32_e32 v25, v81, v25
	v_mul_f32_e64 v33, v81, -v40
	v_mul_f32_e32 v81, v144, v80
	v_mul_f32_e32 v40, v164, v143
	v_mul_f32_e32 v143, 0xbfb8aa3b, v32
	v_mul_f32_e32 v24, v81, v24
	v_mul_f32_e64 v32, v81, -v39
	v_mul_f32_e32 v81, v142, v80
	v_sub_f32_e32 v22, v30, v22
	v_mul_f32_e32 v39, v161, v141
	v_mul_f32_e32 v141, 0xbfb8aa3b, v31
	v_mul_f32_e32 v23, v81, v23
	v_mul_f32_e64 v31, v81, -v38
	v_mul_f32_e32 v81, v158, v139
	v_mul_f32_e32 v139, v140, v80
	v_mul_f32_e32 v140, 0xbfb8aa3b, v30
	v_mul_f32_e32 v22, 0x3fb8aa3b, v22
	v_exp_f32_e32 v140, v140
	v_exp_f32_e32 v22, v22
	v_mul_f32_e64 v30, v139, -v163
	v_sub_f32_e32 v21, v29, v21
	v_mul_f32_e32 v30, v30, v140
	v_mul_f32_e32 v22, v139, v22
	v_mul_f32_e32 v139, v165, v140
	v_mul_f32_e32 v140, 0xbfb8aa3b, v29
	v_mul_f32_e32 v21, 0x3fb8aa3b, v21
	v_exp_f32_e32 v140, v140
	v_exp_f32_e32 v21, v21
	v_mul_f32_e32 v138, v138, v80
	v_mul_f32_e64 v29, v138, -v159
	v_sub_f32_e32 v20, v28, v20
	v_mul_f32_e32 v21, v138, v21
	v_mul_f32_e32 v29, v29, v140
	v_mul_f32_e32 v138, v160, v140
	v_mul_f32_e32 v140, 0xbfb8aa3b, v28
	v_mul_f32_e32 v20, 0x3fb8aa3b, v20
	v_exp_f32_e32 v140, v140
	v_exp_f32_e32 v20, v20
	v_mul_f32_e32 v136, v136, v80
	v_sub_f32_e32 v19, v27, v19
	v_sub_f32_e32 v18, v26, v18
	v_mul_f32_e64 v28, v136, -v155
	v_mul_f32_e32 v19, 0x3fb8aa3b, v19
	v_mul_f32_e32 v18, 0x3fb8aa3b, v18
	v_mul_f32_e32 v20, v136, v20
	v_mul_f32_e32 v28, v28, v140
	v_mul_f32_e32 v136, v156, v140
	v_mul_f32_e32 v134, v134, v80
	v_mul_f32_e32 v140, 0xbfb8aa3b, v27
	v_exp_f32_e32 v19, v19
	v_mul_f32_e32 v80, v132, v80
	v_mul_f32_e32 v132, 0xbfb8aa3b, v26
	v_exp_f32_e32 v18, v18
	v_exp_f32_e32 v145, v145
	v_exp_f32_e32 v143, v143
	v_exp_f32_e32 v141, v141
	v_exp_f32_e32 v140, v140
	v_exp_f32_e32 v132, v132
	v_mul_f32_e32 v19, v134, v19
	v_mul_f32_e64 v27, v134, -v152
	v_mul_f32_e32 v18, v80, v18
	v_mul_f32_e64 v26, v80, -v148
	v_mul_f32_e32 v33, v33, v145
	v_mul_f32_e32 v37, v37, v145
	v_mul_f32_e32 v32, v32, v143
	v_mul_f32_e32 v36, v36, v143
	v_mul_f32_e32 v31, v31, v141
	v_mul_f32_e32 v38, v162, v141
	v_mul_f32_e32 v137, v157, v137
	v_mul_f32_e32 v135, v154, v135
	v_mul_f32_e32 v133, v147, v133
	v_mul_f32_e32 v27, v27, v140
	v_mul_f32_e32 v134, v153, v140
	v_mul_f32_e32 v131, v146, v131
	v_mul_f32_e32 v26, v26, v132
	v_mul_f32_e32 v80, v151, v132
	v_mul_f32_e32 v0, v41, v0
	v_cvt_pk_bf16_f32 v18, v18, v19
	v_cvt_pk_bf16_f32 v19, v20, v21
	v_cvt_pk_bf16_f32 v20, v22, v23
	v_cvt_pk_bf16_f32 v21, v24, v25
	ds_write_b128 v91, v[18:21]
	v_cvt_pk_bf16_f32 v18, v26, v27
	v_cvt_pk_bf16_f32 v19, v28, v29
	v_cvt_pk_bf16_f32 v20, v30, v31
	v_cvt_pk_bf16_f32 v21, v32, v33
	v_cvt_pk_bf16_f32 v22, v80, v134
	v_cvt_pk_bf16_f32 v23, v136, v138
	v_cvt_pk_bf16_f32 v24, v139, v38
	v_cvt_pk_bf16_f32 v25, v36, v37
	v_cvt_pk_bf16_f32 v26, v0, v131
	v_cvt_pk_bf16_f32 v27, v133, v135
	v_cvt_pk_bf16_f32 v28, v137, v81
	v_cvt_pk_bf16_f32 v29, v39, v40
	ds_write_b128 v91, v[18:21] offset:9216
	ds_write_b128 v91, v[22:25] offset:18432
	ds_write_b128 v91, v[26:29] offset:27648
	ds_write_b16 v117, v18 offset:36864
	ds_write_b16_d16_hi v117, v18 offset:37008
	ds_write_b16 v117, v22 offset:46080
	ds_write_b16_d16_hi v117, v22 offset:46224
	s_nop 0
	ds_write_b16 v117, v14 offset:55296
	ds_write_b16_d16_hi v117, v14 offset:55440
	ds_write_b16 v117, v19 offset:37152
	ds_write_b16_d16_hi v117, v19 offset:37296
	ds_write_b16 v117, v23 offset:46368
	ds_write_b16_d16_hi v117, v23 offset:46512
	ds_write_b16 v117, v15 offset:55584
	ds_write_b16_d16_hi v117, v15 offset:55728
	ds_write_b16 v176, v20 offset:37440
	ds_write_b16_d16_hi v176, v20 offset:37584
	ds_write_b16 v176, v24 offset:46656
	ds_write_b16_d16_hi v176, v24 offset:46800
	ds_write_b16 v176, v16 offset:55872
	ds_write_b16_d16_hi v176, v16 offset:56016
	ds_write_b16 v176, v21 offset:37728
	ds_write_b16_d16_hi v176, v21 offset:37872
	ds_write_b16 v176, v25 offset:46944
	ds_write_b16_d16_hi v176, v25 offset:47088
	ds_write_b16 v176, v17 offset:56160
	ds_write_b16_d16_hi v176, v17 offset:56304
	ds_write_b128 v101, v[10:13]
	v_cvt_pk_bf16_f32 v0, v6, v7
	v_cvt_pk_bf16_f32 v10, v8, v9
	ds_write_b16 v87, v0 offset:64512
	ds_write_b16_d16_hi v87, v0 offset:64656
	ds_write_b16 v87, v10 offset:64800
	ds_write_b16_d16_hi v87, v10 offset:64944
	v_cvt_pk_bf16_f32 v0, v2, v3
	v_cvt_pk_bf16_f32 v10, v4, v5
	ds_write_b16 v87, v0 offset:64544
	ds_write_b16_d16_hi v87, v0 offset:64688
	ds_write_b16 v87, v10 offset:64832
	ds_write_b16_d16_hi v87, v10 offset:64976
	s_waitcnt lgkmcnt(0)
	s_barrier
; template <bool PA> ...
;     ...
;             tmp[0] = z4; tmp[1] = z4; mm2(tmp, MAT(0), MAT(2), mt, ntb, r16, kq);
; #pragma unroll
;             for (int i = 0; i < 2; ++i)
; #pragma unroll
;                 for (int e = 0; e < 4; ++e) { const int t = 16 * mt + 4 * kq + e, s = 16 * (ntb + i) + r16; tmp[i][e] = (s < t) ? tmp[i][e] : 0.f; }
;             st_rm(MAT(10), tmp, mt, ntb, r16, kq);
;             f32x4_t X2acc[2]; X2acc[0] = z4; X2acc[1] = z4;
;             if (PA) mm2(X2acc, MAT(0), MAT(12), mt, ntb, r16, kq);
;             if (!PA) {
;             tmp[0] = z4; tmp[1] = z4; mm2(tmp, MAT(3), MAT(1), mt, ntb, r16, kq);
; #pragma unroll
;             for (int i = 0; i < 2; ++i)
; #pragma unroll
;                 for (int e = 0; e < 4; ++e) { const int t = 16 * mt + 4 * kq + e, s = 16 * (ntb + i) + r16; tmp[i][e] = (s <= t) ? tmp[i][e] : 0.f; }
;             st_rm(MAT(11), tmp, mt, ntb, r16, kq);
;             tmp[0] = z4; tmp[1] = z4; mm2(tmp, MAT(3), MAT(2), mt, ntb, r16, kq);
; #pragma unroll
;             for (int i = 0; i < 2; ++i)
; #pragma unroll
;                 for (int e = 0; e < 4; ++e) { const int t = 16 * mt + 4 * kq + e, s = 16 * (ntb + i) + r16; tmp[i][e] = (s <= t) ? tmp[i][e] : 0.f; }
;             st_rm(MAT(12), tmp, mt, ntb, r16, kq);
;             }
;             Xacc[0] = z4; Xacc[1] = z4; mm2(Xacc, MAT(0), MAT(7), mt, ntb, r16, kq);
;             Yacc[0] = z4; Yacc[1] = z4; if (!PA) mm2(Yacc, MAT(3), MAT(7), mt, ntb, r16, kq);
	ds_read_b128 v[178:181], v92
	ds_read_b128 v[182:185], v89 offset:18432
	ds_read_b128 v[186:189], v89 offset:20736
	ds_read_b128 v[190:193], v92 offset:64
	ds_read_b128 v[204:207], v89 offset:18496
	ds_read_b128 v[208:211], v89 offset:20800
	ds_read_b128 v[212:215], v92 offset:27648
	ds_read_b128 v[216:219], v89 offset:9216
	ds_read_b128 v[220:223], v89 offset:11520
	ds_read_b128 v[224:227], v92 offset:27712
	s_nop 0
	s_nop 0
	s_nop 0
	s_waitcnt lgkmcnt(8)
	v_mfma_f32_16x16x32_bf16 v[14:17], v[178:181], v[182:185], 0
	ds_read_b128 v[182:185], v89 offset:9280
	s_add_i32 s12, s12, 1
	s_add_i32 s18, s18, -1
	v_lshl_add_u64 v[78:79], v[78:79], 0, s[34:35]
	s_waitcnt lgkmcnt(8)
	v_mfma_f32_16x16x32_bf16 v[10:13], v[178:181], v[186:189], 0
	ds_read_b128 v[178:181], v89 offset:11584
	ds_read_b128 v[186:189], v92 offset:27648
	s_nop 0
	s_nop 0
	s_cmp_ge_i32 s12, s13
	s_waitcnt lgkmcnt(8)
	v_mfma_f32_16x16x32_bf16 v[14:17], v[190:193], v[204:207], v[14:17]
	ds_read_b128 v[204:207], v89 offset:18432
	s_nop 0
	s_waitcnt lgkmcnt(8)
	v_mfma_f32_16x16x32_bf16 v[10:13], v[190:193], v[208:211], v[10:13]
	ds_read_b128 v[190:193], v89 offset:20736
	ds_read_b128 v[208:211], v92 offset:27712
	s_nop 4
	v_cndmask_b32_e64 v0, 0, v14, s[62:63]
	v_cndmask_b32_e64 v14, v15, 0, s[64:65]
	v_cndmask_b32_e64 v15, 0, v16, s[66:67]
	v_cndmask_b32_e64 v16, 0, v17, s[68:69]
	v_cndmask_b32_e64 v10, 0, v10, s[70:71]
	v_cndmask_b32_e64 v11, v11, 0, s[72:73]
	v_cvt_pk_bf16_f32 v0, v0, v14
	v_cndmask_b32_e64 v12, 0, v12, s[74:75]
	v_cndmask_b32_e64 v13, 0, v13, s[76:77]
	v_cvt_pk_bf16_f32 v14, v15, v16
	ds_write_b16 v102, v0
	ds_write_b16_d16_hi v102, v0 offset:144
	ds_write_b16 v102, v14 offset:288
	ds_write_b16_d16_hi v102, v14 offset:432
	v_cvt_pk_bf16_f32 v0, v10, v11
	v_cvt_pk_bf16_f32 v10, v12, v13
	ds_write_b16 v102, v0 offset:32
	ds_write_b16_d16_hi v102, v0 offset:176
	ds_write_b16 v102, v10 offset:320
	ds_write_b16_d16_hi v102, v10 offset:464
	s_nop 0
	s_nop 0
	s_nop 0
	s_waitcnt lgkmcnt(0)
	v_mfma_f32_16x16x32_bf16 v[14:17], v[212:215], v[216:219], 0
	ds_read_b128 v[216:219], v89 offset:18496
	s_waitcnt lgkmcnt(1)
	v_mfma_f32_16x16x32_bf16 v[10:13], v[212:215], v[220:223], 0
	ds_read_b128 v[212:215], v89 offset:20800
	ds_read_b128 v[220:223], v92
	s_nop 0
	s_nop 0
	s_waitcnt lgkmcnt(3)
	v_mfma_f32_16x16x32_bf16 v[14:17], v[224:227], v[182:185], v[14:17]
	ds_read_b128 v[182:185], v89 offset:64512
	s_nop 0
	s_waitcnt lgkmcnt(4)
	v_mfma_f32_16x16x32_bf16 v[10:13], v[224:227], v[178:181], v[10:13]
	ds_read_b128 v[178:181], v105
	ds_read_b128 v[224:227], v92 offset:64
	s_nop 4
	v_cndmask_b32_e64 v0, v14, 0, s[64:65]
	v_cndmask_b32_e64 v14, v15, 0, s[78:79]
	v_cndmask_b32_e64 v15, v16, 0, s[80:81]
	v_cndmask_b32_e64 v16, v17, 0, s[82:83]
	v_cndmask_b32_e64 v10, v10, 0, s[72:73]
	v_cndmask_b32_e64 v11, v11, 0, s[84:85]
	v_cvt_pk_bf16_f32 v0, v0, v14
	v_cndmask_b32_e64 v12, v12, 0, s[86:87]
	v_cndmask_b32_e64 v13, v13, 0, s[88:89]
	v_cvt_pk_bf16_f32 v14, v15, v16
	ds_write_b16 v103, v0
	ds_write_b16_d16_hi v103, v0 offset:144
	ds_write_b16 v103, v14 offset:288
	ds_write_b16_d16_hi v103, v14 offset:432
	v_cvt_pk_bf16_f32 v0, v10, v11
	v_cvt_pk_bf16_f32 v10, v12, v13
	ds_write_b16 v103, v0 offset:32
	ds_write_b16_d16_hi v103, v0 offset:176
	ds_write_b16 v103, v10 offset:320
	ds_write_b16_d16_hi v103, v10 offset:464
	s_nop 0
	s_nop 0
	s_nop 0
	s_waitcnt lgkmcnt(0)
	v_mfma_f32_16x16x32_bf16 v[14:17], v[186:189], v[204:207], 0
	ds_read_b128 v[204:207], v92 offset:27648
	s_waitcnt lgkmcnt(1)
	v_mfma_f32_16x16x32_bf16 v[10:13], v[186:189], v[190:193], 0
	s_nop 0
	s_nop 0
	s_waitcnt lgkmcnt(1)
	v_mfma_f32_16x16x32_bf16 v[14:17], v[208:211], v[216:219], v[14:17]
	s_nop 0
	s_waitcnt lgkmcnt(1)
	v_mfma_f32_16x16x32_bf16 v[10:13], v[208:211], v[212:215], v[10:13]
	s_nop 4
	v_cndmask_b32_e64 v0, v14, 0, s[64:65]
	v_cndmask_b32_e64 v14, v15, 0, s[78:79]
	v_cndmask_b32_e64 v15, v16, 0, s[80:81]
	v_cndmask_b32_e64 v16, v17, 0, s[82:83]
	v_cndmask_b32_e64 v10, v10, 0, s[72:73]
	v_cndmask_b32_e64 v11, v11, 0, s[84:85]
	v_cvt_pk_bf16_f32 v0, v0, v14
	v_cndmask_b32_e64 v12, v12, 0, s[86:87]
	v_cndmask_b32_e64 v13, v13, 0, s[88:89]
	v_cvt_pk_bf16_f32 v14, v15, v16
	ds_write_b16 v104, v0
	ds_write_b16_d16_hi v104, v0 offset:144
	ds_write_b16 v104, v14 offset:288
	ds_write_b16_d16_hi v104, v14 offset:432
	v_cvt_pk_bf16_f32 v0, v10, v11
	v_cvt_pk_bf16_f32 v10, v12, v13
	ds_write_b16 v104, v0 offset:32
	ds_write_b16_d16_hi v104, v0 offset:176
	ds_write_b16 v104, v10 offset:320
	ds_write_b16_d16_hi v104, v10 offset:464
	s_nop 0
	s_nop 0
	s_nop 0
	s_nop 0
	ds_read_b128 v[30:33], v89 offset:64576
	ds_read_b128 v[36:39], v106
	s_waitcnt lgkmcnt(2)
	v_mfma_f32_16x16x32_bf16 v[18:21], v[220:223], v[182:185], 0
	s_waitcnt lgkmcnt(2)
	v_mfma_f32_16x16x32_bf16 v[10:13], v[220:223], v[178:181], 0
	s_waitcnt lgkmcnt(1)
	v_mfma_f32_16x16x32_bf16 v[18:21], v[224:227], v[30:33], v[18:21]
	s_waitcnt lgkmcnt(0)
	v_mfma_f32_16x16x32_bf16 v[10:13], v[224:227], v[36:39], v[10:13]
	s_nop 0
	s_waitcnt lgkmcnt(0)
	v_mfma_f32_16x16x32_bf16 v[14:17], v[204:207], v[182:185], 0
	v_mfma_f32_16x16x32_bf16 v[22:25], v[204:207], v[178:181], 0
	ds_read_b128 v[26:29], v92 offset:27712
	s_waitcnt lgkmcnt(0)
	s_barrier
; template <bool PA> ...
;     ...
;             const bf16* Tm = haveT ? MAT(9) : MAT(3);
;             mm2(Xacc, MAT(10), MAT(6), mt, ntb, r16, kq);
;             st_tr(MAT(7), Xacc, mt, ntb, r16, kq);
;             if (PA) st_tr(MAT(11), X2acc, mt, ntb, r16, kq);
;             __syncthreads();
;             tmp[0] = z4; tmp[1] = z4; mm2(tmp, Tm, MAT(7), mt, ntb, r16, kq);
;             st_tr(MAT(8), tmp, mt, ntb, r16, kq);
;             if (PA) { tmp[0] = z4; tmp[1] = z4; mm2(tmp, MAT(3), MAT(11), mt, ntb, r16, kq); st_tr(MAT(12), tmp, mt, ntb, r16, kq); }
;             __syncthreads();
;             if (!PA) { mm2(Yacc, MAT(11), MAT(8), mt, ntb, r16, kq); mm2(Yacc, MAT(12), MAT(6), mt, ntb, r16, kq);
;             st_rm(MAT(7), Yacc, mt, ntb, r16, kq); }
;             if (PA) mm2(S2acc, MAT(12), MAT(4), mt, ntb, r16, kq);
;             mm2(Sacc, MAT(8), MAT(4), mt, ntb, r16, kq); mm2(Sacc, MAT(6), MAT(5), mt, ntb, r16, kq);
; #pragma unroll
;             for (int i = 0; i < 2; ++i) { const float wk = wc[16 * (ntb + i) + r16];
; #pragma unroll
;                 for (int e = 0; e < 4; ++e) { Sacc[i][e] *= wk; S2acc[i][e] *= wk; } }
;             __syncthreads();
;             if (!PA) { const size_t orow = cbase + (d ? 63 - j : j); *(u32x4_t*)(Op + orow * 1024 + hc8) = *(const u32x4_t*)(MAT(7) + j * 72 + c8); }
	ds_read_b128 v[178:181], v107
	ds_read_b128 v[182:185], v89 offset:55296
	ds_read_b128 v[186:189], v89 offset:57600
	ds_read_b128 v[190:193], v107 offset:64
	ds_read_b128 v[204:207], v89 offset:55360
	ds_read_b128 v[208:211], v89 offset:57664
	v_mfma_f32_16x16x32_bf16 v[14:17], v[26:29], v[30:33], v[14:17]
	v_mfma_f32_16x16x32_bf16 v[22:25], v[26:29], v[36:39], v[22:25]
	s_nop 0
	s_nop 0
	s_waitcnt lgkmcnt(4)
	v_mfma_f32_16x16x32_bf16 v[18:21], v[178:181], v[182:185], v[18:21]
	s_nop 0
	s_waitcnt lgkmcnt(3)
	v_mfma_f32_16x16x32_bf16 v[10:13], v[178:181], v[186:189], v[10:13]
	s_nop 0
	s_nop 0
	s_waitcnt lgkmcnt(1)
	v_mfma_f32_16x16x32_bf16 v[18:21], v[190:193], v[204:207], v[18:21]
	s_nop 0
	s_waitcnt lgkmcnt(0)
	v_mfma_f32_16x16x32_bf16 v[10:13], v[190:193], v[208:211], v[10:13]
	s_nop 4
	v_cvt_pk_bf16_f32 v18, v18, v19
	v_cvt_pk_bf16_f32 v19, v20, v21
	ds_write_b64 v108, v[18:19] offset:64512
	v_cvt_pk_bf16_f32 v10, v10, v11
	v_cvt_pk_bf16_f32 v11, v12, v13
	ds_write_b64 v109, v[10:11]
	s_waitcnt lgkmcnt(0)
	s_barrier
	ds_read_b128 v[178:181], v110
	ds_read_b128 v[182:185], v89 offset:64512
	ds_read_b128 v[186:189], v105
	ds_read_b128 v[190:193], v110 offset:64
	ds_read_b128 v[204:207], v89 offset:64576
	ds_read_b128 v[208:211], v106
	s_nop 0
	s_nop 0
	s_nop 0
	s_waitcnt lgkmcnt(4)
	v_mfma_f32_16x16x32_bf16 v[18:21], v[178:181], v[182:185], 0
	s_waitcnt lgkmcnt(3)
	v_mfma_f32_16x16x32_bf16 v[10:13], v[178:181], v[186:189], 0
	s_nop 0
	s_nop 0
	s_waitcnt lgkmcnt(1)
	v_mfma_f32_16x16x32_bf16 v[18:21], v[190:193], v[204:207], v[18:21]
	s_nop 0
	s_waitcnt lgkmcnt(0)
	v_mfma_f32_16x16x32_bf16 v[10:13], v[190:193], v[208:211], v[10:13]
	v_mov_b32_e32 v26, v190
	v_mov_b32_e32 v27, v191
	v_mov_b32_e32 v28, v192
	v_mov_b32_e32 v29, v193
	v_mov_b32_e32 v30, v208
	v_mov_b32_e32 v31, v209
	v_mov_b32_e32 v32, v210
	v_mov_b32_e32 v33, v211
	s_nop 4
	v_cvt_pk_bf16_f32 v18, v18, v19
	v_cvt_pk_bf16_f32 v19, v20, v21
	ds_write_b64 v111, v[18:19]
	v_cvt_pk_bf16_f32 v10, v10, v11
	v_cvt_pk_bf16_f32 v11, v12, v13
	ds_write_b64 v111, v[10:11] offset:2304
	s_waitcnt lgkmcnt(0)
	s_barrier
	ds_read_b128 v[178:181], v112
	ds_read_b128 v[182:185], v113
	ds_read_b128 v[186:189], v113 offset:2304
	ds_read_b128 v[190:193], v112 offset:64
	ds_read_b128 v[204:207], v113 offset:64
	ds_read_b128 v[208:211], v113 offset:2368
	ds_read_b128 v[212:215], v114
	ds_read_b128 v[216:219], v89 offset:55296
	ds_read_b128 v[220:223], v89 offset:57600
	ds_read_b128 v[224:227], v114 offset:64
	s_nop 0
	s_nop 0
	s_waitcnt lgkmcnt(8)
	v_mfma_f32_16x16x32_bf16 v[14:17], v[178:181], v[182:185], v[14:17]
	ds_read_b128 v[182:185], v89 offset:55360
	s_nop 0
	s_waitcnt lgkmcnt(8)
	v_mfma_f32_16x16x32_bf16 v[10:13], v[178:181], v[186:189], v[22:25]
	ds_read_b128 v[178:181], v89 offset:57664
	ds_read_b128 v[186:189], v115
	s_nop 0
	s_nop 1
	s_nop 0
	s_waitcnt lgkmcnt(8)
	v_mfma_f32_16x16x32_bf16 v[14:17], v[190:193], v[204:207], v[14:17]
	ds_read_b128 v[204:207], v89 offset:36864
	s_nop 0
	s_waitcnt lgkmcnt(8)
	v_mfma_f32_16x16x32_bf16 v[10:13], v[190:193], v[208:211], v[10:13]
	ds_read_b128 v[190:193], v89 offset:39168
	ds_read_b128 v[208:211], v115 offset:64
	s_nop 0
	s_nop 0
	s_waitcnt lgkmcnt(8)
	v_mfma_f32_16x16x32_bf16 v[14:17], v[212:215], v[216:219], v[14:17]
	ds_read_b128 v[216:219], v89 offset:36928
	s_nop 0
	s_waitcnt lgkmcnt(8)
	v_mfma_f32_16x16x32_bf16 v[10:13], v[212:215], v[220:223], v[10:13]
	ds_read_b128 v[212:215], v89 offset:39232
	ds_read_b128 v[220:223], v92 offset:55296
	s_nop 0
	s_nop 0
	s_waitcnt lgkmcnt(8)
	v_mfma_f32_16x16x32_bf16 v[14:17], v[224:227], v[182:185], v[14:17]
	ds_read_b128 v[182:185], v89 offset:46080
	s_nop 0
	s_waitcnt lgkmcnt(8)
	v_mfma_f32_16x16x32_bf16 v[10:13], v[224:227], v[178:181], v[10:13]
	v_mov_b32_e32 v18, v224
	v_mov_b32_e32 v19, v225
	v_mov_b32_e32 v20, v226
	v_mov_b32_e32 v21, v227
	v_mov_b32_e32 v22, v178
	v_mov_b32_e32 v23, v179
	v_mov_b32_e32 v24, v180
	v_mov_b32_e32 v25, v181
	ds_read_b128 v[178:181], v89 offset:48384
	ds_read_b128 v[224:227], v92 offset:55360
	s_nop 4
	v_cvt_pk_bf16_f32 v0, v14, v15
	v_cvt_pk_bf16_f32 v14, v16, v17
	ds_write_b16 v87, v0 offset:64512
	ds_write_b16_d16_hi v87, v0 offset:64656
	ds_write_b16 v87, v14 offset:64800
	ds_write_b16_d16_hi v87, v14 offset:64944
	v_cvt_pk_bf16_f32 v0, v10, v11
	v_cvt_pk_bf16_f32 v10, v12, v13
	ds_write_b16 v87, v0 offset:64544
	ds_write_b16_d16_hi v87, v0 offset:64688
	ds_write_b16 v87, v10 offset:64832
	ds_write_b16_d16_hi v87, v10 offset:64976
	s_nop 0
	s_nop 0
	s_waitcnt lgkmcnt(0)
	v_mfma_f32_16x16x32_bf16 v[6:9], v[186:189], v[204:207], v[6:9]
	ds_read_b128 v[204:207], v89 offset:46144
	s_nop 0
	s_waitcnt lgkmcnt(1)
	v_mfma_f32_16x16x32_bf16 v[2:5], v[186:189], v[190:193], v[2:5]
	ds_read_b128 v[186:189], v89 offset:48448
	s_nop 0
	s_nop 0
	s_waitcnt lgkmcnt(2)
	v_mfma_f32_16x16x32_bf16 v[6:9], v[208:211], v[216:219], v[6:9]
	s_nop 0
	s_waitcnt lgkmcnt(2)
	v_mfma_f32_16x16x32_bf16 v[2:5], v[208:211], v[212:215], v[2:5]
	s_nop 0
	s_nop 0
	s_waitcnt lgkmcnt(2)
	v_mfma_f32_16x16x32_bf16 v[6:9], v[220:223], v[182:185], v[6:9]
	s_nop 0
	s_waitcnt lgkmcnt(2)
	v_mfma_f32_16x16x32_bf16 v[2:5], v[220:223], v[178:181], v[2:5]
	s_nop 0
	s_nop 0
	ds_read_b32 v0, v127
	s_waitcnt lgkmcnt(2)
	v_mfma_f32_16x16x32_bf16 v[6:9], v[224:227], v[204:207], v[6:9]
	s_nop 0
	s_waitcnt lgkmcnt(0)
	v_mfma_f32_16x16x32_bf16 v[2:5], v[224:227], v[186:189], v[2:5]
	v_mov_b32_e32 v16, v188
	v_mov_b32_e32 v17, v189
	s_nop 4
	v_mul_f32_e64 v6, v6, v0
	v_mul_f32_e64 v7, v7, v0
	v_pk_mul_f32 v[8:9], v[8:9], v[0:1] op_sel_hi:[1,0]
	ds_read_b32 v0, v128
	s_waitcnt lgkmcnt(0)
	s_barrier
	ds_read_b128 v[10:13], v91 offset:64512
	v_pk_mul_f32 v[2:3], v[2:3], v[0:1] op_sel_hi:[1,0]
	v_pk_mul_f32 v[4:5], v[4:5], v[0:1] op_sel_hi:[1,0]
	v_lshl_add_u64 v[14:15], v[34:35], 1, v[76:77]
	s_waitcnt lgkmcnt(0)
	global_store_dwordx4 v[14:15], v[10:13], off
	s_cbranch_scc1 .LBB0_128
; template <bool PA> ...
;     ...
;             const int cidx = d ? nch - 1 - p : p; const int cbase = seqbase + cidx * 64;
;             float rv[8], kk[8], av[8], kd[8], lw[8]; u32x4_t tld = (u32x4_t){0u, 0u, 0u, 0u}, vraw = (u32x4_t){0u, 0u, 0u, 0u};
;             {
;                 const size_t row = cbase + (d ? 63 - j : j);
;                 asm volatile("" ::: "memory");
;                 if (haveT && tlow) tld = *(const u32x4_t*)(tbuf + ((size_t)strm * NCHA + p) * 2304 + tunit * 8);
;                 *(u32x4_t*)(MAT(4) + j * 72 + c8) = *(const u32x4_t*)(HWb + row * 128 + d * 64 + c8);
;                 *(u32x4_t*)(MAT(5) + j * 72 + c8) = *(const u32x4_t*)(HAb + row * 128 + d * 64 + c8);
;                 const u32x4_t rw = *(const u32x4_t*)(Rb + row * 1024 + hc8), kw = *(const u32x4_t*)(Kb + row * 1024 + hc8), vw = *(const u32x4_t*)(Vb + row * 1024 + hc8);
;                 __syncthreads();
;                 { f32x4_t za[2], xa[2]; za[0] = (f32x4_t){0.f, 0.f, 0.f, 0.f}; za[1] = za[0]; xa[0] = za[0]; xa[1] = za[0];
;                   mm2(za, MAT(4), w2T, mt, ntb, r16, kq); mm2(xa, MAT(5), a2T, mt, ntb, r16, kq);
; #pragma unroll
;                   for (int i = 0; i < 2; ++i)
; #pragma unroll
;                       for (int e = 0; e < 4; ++e) { zbuf[(16 * mt + 4 * kq + e) * 64 + 16 * (ntb + i) + r16] = za[i][e]; abuf[(16 * mt + 4 * kq + e) * 64 + 16 * (ntb + i) + r16] = xa[i][e]; } }
;                 __syncthreads();
;                 const unsigned rwa[4] = {rw.x, rw.y, rw.z, rw.w}, kwa[4] = {kw.x, kw.y, kw.z, kw.w};
;                 float kv[8], z[8], aa[8];
; #pragma unroll
;                 for (int q = 0; q < 4; ++q) { rv[2 * q] = __uint_as_float(rwa[q] << 16); rv[2 * q + 1] = __uint_as_float(rwa[q] & 0xffff0000u); kv[2 * q] = __uint_as_float(kwa[q] << 16); kv[2 * q + 1] = __uint_as_float(kwa[q] & 0xffff0000u);
;                 }
;                 vraw = vw;
;                 { const f32x4_t z0 = *(const f32x4_t*)(zbuf + j * 64 + c8), z1 = *(const f32x4_t*)(zbuf + j * 64 + c8 + 4), x0 = *(const f32x4_t*)(abuf + j * 64 + c8), x1 = *(const f32x4_t*)(abuf + j * 64 + c8 + 4);
; #pragma unroll
;                   for (int e = 0; e < 4; ++e) { z[e] = cst[c8 + e] + z0[e]; z[4 + e] = cst[c8 + 4 + e] + z1[e]; aa[e] = cst[64 + c8 + e] + x0[e]; aa[4 + e] = cst[64 + c8 + 4 + e] + x1[e]; } }
;                 asm volatile("" ::: "memory");
.LBB0_153:
	s_nop 0
	s_waitcnt vmcnt(2)
	ds_write_b128 v91, v[232:235] offset:36864
	ds_write_b128 v91, v[236:239] offset:46080
	v_mov_b32_e32 v10, v228
	v_mov_b32_e32 v11, v229
	v_mov_b32_e32 v12, v230
	v_mov_b32_e32 v13, v231
	v_mov_b32_e32 v18, v240
	v_mov_b32_e32 v19, v241
	v_mov_b32_e32 v20, v242
	v_mov_b32_e32 v21, v243
	v_mov_b32_e32 v22, v244
	v_mov_b32_e32 v23, v245
	v_mov_b32_e32 v24, v246
	v_mov_b32_e32 v25, v247
	v_mov_b32_e32 v14, v248
	v_mov_b32_e32 v15, v249
	v_mov_b32_e32 v16, v250
	v_mov_b32_e32 v17, v251
	s_and_b64 s[0:1], vcc, exec
	s_cselect_b32 s0, s12, s18
	s_cselect_b32 s1, 64, 0xffffffc0
	v_lshl_add_u32 v80, s0, 6, v130
	v_ashrrev_i32_e32 v81, 31, v80
	s_add_i32 s0, s12, 1
	s_cmp_lt_i32 s0, s13
	s_cselect_b32 s1, s1, 0
	v_add_u32_e32 v226, s1, v80
	s_and_saveexec_b64 s[0:1], s[36:37]
	global_load_dwordx4 v[228:231], v[78:79], off
	s_or_b64 exec, exec, s[0:1]
	v_ashrrev_i32_e32 v227, 31, v226
	v_lshlrev_b64 v[224:225], 8, v[226:227]
	v_lshl_add_u64 v[222:223], v[66:67], 0, v[224:225]
	global_load_dwordx4 v[232:235], v[222:223], off
	v_lshl_add_u64 v[222:223], v[68:69], 0, v[224:225]
	global_load_dwordx4 v[236:239], v[222:223], off
	v_lshlrev_b64 v[224:225], 11, v[226:227]
	v_lshl_add_u64 v[222:223], v[70:71], 0, v[224:225]
	global_load_dwordx4 v[240:243], v[222:223], off
	v_lshl_add_u64 v[222:223], v[72:73], 0, v[224:225]
	global_load_dwordx4 v[244:247], v[222:223], off
	v_lshl_add_u64 v[222:223], v[74:75], 0, v[224:225]
	global_load_dwordx4 v[248:251], v[222:223], off
	s_waitcnt lgkmcnt(0)
	s_barrier
	ds_read_b128 v[178:181], v92 offset:36864
	ds_read_b128 v[182:185], v93
	ds_read_b128 v[186:189], v93 offset:2304
	ds_read_b128 v[190:193], v92 offset:36928
	ds_read_b128 v[204:207], v93 offset:64
	ds_read_b128 v[208:211], v93 offset:2368
	ds_read_b128 v[212:215], v92 offset:46080
	ds_read_b128 v[216:219], v94
	ds_read_b128 v[220:223], v94 offset:2304
	ds_read_b128 v[224:227], v92 offset:46144
	s_nop 0
	s_nop 0
	s_nop 0
	s_waitcnt lgkmcnt(8)
	v_mfma_f32_16x16x32_bf16 v[30:33], v[178:181], v[182:185], 0
	ds_read_b128 v[182:185], v94 offset:64
	s_nop 0
	v_lshlrev_b32_e32 v0, 16, v18
	s_waitcnt lgkmcnt(8)
	v_mfma_f32_16x16x32_bf16 v[26:29], v[178:181], v[186:189], 0
	ds_read_b128 v[178:181], v94 offset:2368
	s_nop 0
	s_nop 0
	v_and_b32_e32 v131, 0xffff0000, v18
	s_nop 0
	v_and_b32_e32 v162, 0xffff0000, v24
	s_waitcnt lgkmcnt(7)
	v_mfma_f32_16x16x32_bf16 v[30:33], v[190:193], v[204:207], v[30:33]
	s_nop 0
	v_lshlrev_b32_e32 v141, 16, v21
	v_and_b32_e32 v143, 0xffff0000, v21
	s_waitcnt lgkmcnt(6)
	v_mfma_f32_16x16x32_bf16 v[26:29], v[190:193], v[208:211], v[26:29]
	s_nop 0
	s_nop 0
	s_nop 0
	v_lshlrev_b32_e32 v158, 16, v25
	s_waitcnt lgkmcnt(4)
	v_mfma_f32_16x16x32_bf16 v[38:41], v[212:215], v[216:219], 0
	v_and_b32_e32 v154, 0xffff0000, v25
	s_waitcnt lgkmcnt(3)
	v_mfma_f32_16x16x32_bf16 v[34:37], v[212:215], v[220:223], 0
	s_nop 0
	s_nop 0
	s_waitcnt lgkmcnt(1)
	v_mfma_f32_16x16x32_bf16 v[38:41], v[224:227], v[182:185], v[38:41]
	s_nop 0
	s_waitcnt lgkmcnt(0)
	v_mfma_f32_16x16x32_bf16 v[34:37], v[224:227], v[178:181], v[34:37]
	s_nop 4
	ds_write2st64_b32 v119, v30, v38 offset1:64
	ds_write2st64_b32 v120, v31, v39 offset1:64
	ds_write2st64_b32 v121, v32, v40 offset1:64
	ds_write2st64_b32 v122, v33, v41 offset1:64
	ds_write2st64_b32 v123, v26, v34 offset1:64
	ds_write2st64_b32 v124, v27, v35 offset1:64
	ds_write2st64_b32 v125, v28, v36 offset1:64
	ds_write2st64_b32 v126, v29, v37 offset1:64
	s_waitcnt lgkmcnt(0)
	s_barrier
	v_lshlrev_b32_e32 v39, 16, v22
	v_and_b32_e32 v36, 0xffff0000, v22
	v_lshlrev_b32_e32 v133, 16, v19
	v_and_b32_e32 v135, 0xffff0000, v19
	v_lshlrev_b32_e32 v35, 16, v23
	v_and_b32_e32 v34, 0xffff0000, v23
	v_lshlrev_b32_e32 v137, 16, v20
	v_and_b32_e32 v139, 0xffff0000, v20
	v_lshlrev_b32_e32 v38, 16, v24
	ds_read_b128 v[18:21], v95
	ds_read_b128 v[22:25], v95 offset:16
	ds_read_b128 v[144:147], v95 offset:16384
	ds_read_b128 v[148:151], v95 offset:16400
	ds_read_b128 v[26:29], v96
	ds_read_b128 v[30:33], v96 offset:16
	ds_read_b128 v[164:167], v96 offset:256
	ds_read_b128 v[168:171], v96 offset:272
	s_waitcnt lgkmcnt(1)
	v_add_f32_e32 v153, v144, v164
	s_waitcnt lgkmcnt(0)
	v_add_f32_e32 v37, v148, v168
	v_add_f32_e32 v152, v145, v165
	v_add_f32_e32 v164, v149, v169
	v_add_f32_e32 v41, v146, v166
	v_add_f32_e32 v161, v150, v170
	v_add_f32_e32 v40, v147, v167
	v_add_f32_e32 v157, v151, v171
	ds_read_b128 v[144:147], v96 offset:512
	ds_read_b128 v[148:151], v96 offset:528
	ds_read_b128 v[168:171], v96 offset:768
	ds_read_b128 v[172:175], v96 offset:1024
	s_waitcnt lgkmcnt(3)
	v_mul_f32_e32 v134, v145, v36
	v_mul_f32_e32 v132, v144, v39
	v_mul_f32_e32 v155, v134, v134
	v_fmac_f32_e32 v155, v132, v132
	v_mul_f32_e32 v136, v146, v35
	v_fmac_f32_e32 v155, v136, v136
	v_mul_f32_e32 v138, v147, v34
	v_fmac_f32_e32 v155, v138, v138
	s_waitcnt lgkmcnt(2)
	v_mul_f32_e32 v140, v148, v38
	v_and_b32_e32 v147, 64, v198
	v_fmac_f32_e32 v155, v140, v140
	v_mul_f32_e32 v142, v149, v162
	v_xor_b32_e32 v146, 1, v198
	v_add_u32_e32 v147, 64, v147
	v_fmac_f32_e32 v155, v142, v142
	v_mul_f32_e32 v144, v150, v158
	v_cmp_lt_i32_e64 s[92:93], v146, v147
	v_fmac_f32_e32 v155, v144, v144
	v_mul_f32_e32 v145, v151, v154
	v_cndmask_b32_e64 v146, v198, v146, s[92:93]
	v_fmac_f32_e32 v155, v145, v145
	v_lshlrev_b32_e32 v146, 2, v146
	ds_bpermute_b32 v148, v146, v155
	v_xor_b32_e32 v149, 2, v198
	v_cmp_lt_i32_e64 s[92:93], v149, v147
	s_waitcnt lgkmcnt(0)
	v_add_f32_e32 v148, v155, v148
	v_cndmask_b32_e64 v149, v198, v149, s[92:93]
	v_lshlrev_b32_e32 v166, 2, v149
	ds_bpermute_b32 v149, v166, v148
	s_waitcnt lgkmcnt(0)
; __device__ __forceinline__ float sigmoidf_(float x) { return __builtin_amdgcn_rcpf(1.0f + __expf(-x)); }
; template <bool PA> ...
;     ...
;                 float ss = 0.f, bsum = 0.f;
; #pragma unroll
;                 for (int e = 0; e < 8; ++e) { kk[e] = kv[e] * cst[128 + c8 + e]; ss += kk[e] * kk[e]; }
;                 ss += __shfl_xor(ss, 1); ss += __shfl_xor(ss, 2); ss += __shfl_xor(ss, 4);
;                 const float inv = rsqrtf(fmaxf(ss, 1e-24f));
; #pragma unroll
;                 for (int e = 0; e < 8; ++e) { av[e] = sigmoidf_(aa[e]); lw[e] = -0.6065306597f * sigmoidf_(z[e]); kd[e] = kv[e] * (1.0f + (av[e] - 1.0f) * cst[192 + c8 + e]); kk[e] *= inv; bsum += rv[e] * kd[e] * cst[256 + c8 + e]; }
;                 bsum += __shfl_xor(bsum, 1); bsum += __shfl_xor(bsum, 2); bsum += __shfl_xor(bsum, 4);
;                 if (!PA && part == 0) beta[((size_t)d * SLAB + row) * 16 + head] = bsum;
;                 *(f32x4_t*)(cumb + j * 64 + c8) = (f32x4_t){lw[0], lw[1], lw[2], lw[3]}; *(f32x4_t*)(cumb + j * 64 + c8 + 4) = (f32x4_t){lw[4], lw[5], lw[6], lw[7]};
;             }
;             __syncthreads();
;             { const int c = tid & 63, sg = tid >> 6; float run = 0.f;
; #pragma unroll
;               for (int i = 0; i < 8; ++i) { run += cumb[(8 * sg + i) * 64 + c]; cumb[(8 * sg + i) * 64 + c] = run; }
;               segtot[sg * 64 + c] = run; }
;             __syncthreads();
;             { const int c = tid & 63, sg = tid >> 6; float off = 0.f;
; #pragma unroll
;               for (int s = 0; s < 7; ++s) off += (s < sg) ? segtot[s * 64 + c] : 0.f;
; #pragma unroll
;               for (int i = 0; i < 8; ++i) cumb[(8 * sg + i) * 64 + c] += off; }
	v_add_f32_e32 v149, v148, v149
	v_xor_b32_e32 v148, 4, v198
	v_cmp_lt_i32_e64 s[92:93], v148, v147
	s_nop 1
	v_cndmask_b32_e64 v147, v198, v148, s[92:93]
	v_mul_f32_e32 v148, 0xbfb8aa3b, v153
	v_exp_f32_e32 v148, v148
	v_lshlrev_b32_e32 v147, 2, v147
	ds_bpermute_b32 v150, v147, v149
	v_add_f32_e32 v148, 1.0, v148
	v_rcp_f32_e32 v148, v148
	s_nop 0
	v_add_f32_e32 v151, -1.0, v148
	v_fma_f32 v151, v151, v168, 1.0
	v_mul_f32_e32 v151, v151, v39
	v_mul_f32_e32 v39, v151, v0
	v_fma_f32 v167, v172, v39, 0
	v_mul_f32_e32 v39, 0xbfb8aa3b, v152
	v_exp_f32_e32 v39, v39
	s_nop 0
	v_add_f32_e32 v39, 1.0, v39
	v_rcp_f32_e32 v152, v39
	s_nop 0
	v_add_f32_e32 v39, -1.0, v152
	v_fma_f32 v39, v39, v169, 1.0
	v_mul_f32_e32 v153, v39, v36
	v_mul_f32_e32 v36, v153, v131
	v_fmac_f32_e32 v167, v173, v36
	v_mul_f32_e32 v36, 0xbfb8aa3b, v41
	v_exp_f32_e32 v36, v36
	s_nop 0
	v_add_f32_e32 v36, 1.0, v36
	v_rcp_f32_e32 v155, v36
	s_nop 0
	v_add_f32_e32 v36, -1.0, v155
	v_fma_f32 v36, v36, v170, 1.0
	v_mul_f32_e32 v156, v36, v35
	v_mul_f32_e32 v35, v156, v133
	v_fmac_f32_e32 v167, v174, v35
	v_mul_f32_e32 v35, 0xbfb8aa3b, v40
	v_exp_f32_e32 v35, v35
	s_nop 0
	v_add_f32_e32 v35, 1.0, v35
	v_rcp_f32_e32 v159, v35
	s_nop 0
	v_add_f32_e32 v35, -1.0, v159
	v_fma_f32 v35, v35, v171, 1.0
	v_mul_f32_e32 v160, v35, v34
	v_mul_f32_e32 v34, v160, v135
	v_fmac_f32_e32 v167, v175, v34
	v_mul_f32_e32 v34, 0xbfb8aa3b, v37
	v_exp_f32_e32 v34, v34
	s_nop 0
	v_add_f32_e32 v34, 1.0, v34
	v_rcp_f32_e32 v163, v34
	ds_read_b128 v[34:37], v96 offset:784
	v_add_f32_e32 v39, -1.0, v163
	s_waitcnt lgkmcnt(0)
	v_fma_f32 v34, v39, v34, 1.0
	v_mul_f32_e32 v165, v34, v38
	ds_read_b128 v[38:41], v96 offset:1040
	v_mul_f32_e32 v34, v165, v137
	s_waitcnt lgkmcnt(0)
	v_fmac_f32_e32 v167, v38, v34
	v_mul_f32_e32 v34, 0xbfb8aa3b, v164
	v_exp_f32_e32 v34, v34
	s_nop 0
	v_add_f32_e32 v34, 1.0, v34
	v_rcp_f32_e32 v38, v34
	s_nop 0
	v_add_f32_e32 v34, -1.0, v38
	v_fma_f32 v34, v34, v35, 1.0
	v_mul_f32_e32 v162, v34, v162
	v_mul_f32_e32 v34, v162, v139
	v_fmac_f32_e32 v167, v39, v34
	v_mul_f32_e32 v34, 0xbfb8aa3b, v161
	v_exp_f32_e32 v34, v34
	s_nop 0
	v_add_f32_e32 v34, 1.0, v34
	v_rcp_f32_e32 v39, v34
	s_nop 0
	v_add_f32_e32 v34, -1.0, v39
	v_fma_f32 v34, v34, v36, 1.0
	v_mul_f32_e32 v36, v34, v158
	v_mul_f32_e32 v34, v36, v141
	v_fmac_f32_e32 v167, v40, v34
	v_mul_f32_e32 v34, 0xbfb8aa3b, v157
	v_exp_f32_e32 v34, v34
	s_nop 0
	v_add_f32_e32 v34, 1.0, v34
	v_rcp_f32_e32 v40, v34
	s_nop 0
	v_add_f32_e32 v34, -1.0, v40
	v_fma_f32 v34, v34, v37, 1.0
	v_mul_f32_e32 v37, v34, v154
	v_mul_f32_e32 v34, v37, v143
	v_fmac_f32_e32 v167, v41, v34
	ds_bpermute_b32 v34, v146, v167
	s_waitcnt lgkmcnt(0)
	v_add_f32_e32 v34, v167, v34
	ds_bpermute_b32 v35, v166, v34
	s_waitcnt lgkmcnt(0)
	v_add_f32_e32 v34, v34, v35
	ds_bpermute_b32 v35, v147, v34
	s_and_saveexec_b64 s[0:1], s[44:45]
	s_cbranch_execz .LBB0_157
	v_lshl_add_u64 v[146:147], s[24:25], 0, v[80:81]
	v_lshlrev_b64 v[146:147], 6, v[146:147]
	v_lshl_add_u64 v[146:147], s[20:21], 0, v[146:147]
	s_waitcnt lgkmcnt(0)
	v_add_f32_e32 v34, v34, v35
	global_store_dword v[146:147], v34, off
.LBB0_157:
	s_or_b64 exec, exec, s[0:1]
	v_add_f32_e32 v18, v18, v26
	v_add_f32_e32 v19, v19, v27
	v_add_f32_e32 v20, v20, v28
	v_add_f32_e32 v21, v21, v29
	v_add_f32_e32 v22, v22, v30
	v_add_f32_e32 v23, v23, v31
	v_add_f32_e32 v24, v24, v32
	v_add_f32_e32 v25, v25, v33
	v_mul_f32_e32 v18, 0xbfb8aa3b, v18
	v_mul_f32_e32 v19, 0xbfb8aa3b, v19
	v_mul_f32_e32 v20, 0xbfb8aa3b, v20
	v_mul_f32_e32 v21, 0xbfb8aa3b, v21
	v_exp_f32_e32 v18, v18
	v_exp_f32_e32 v19, v19
	v_exp_f32_e32 v20, v20
	v_exp_f32_e32 v21, v21
	v_mul_f32_e32 v22, 0xbfb8aa3b, v22
	v_mul_f32_e32 v23, 0xbfb8aa3b, v23
	v_mul_f32_e32 v24, 0xbfb8aa3b, v24
	v_mul_f32_e32 v25, 0xbfb8aa3b, v25
	v_exp_f32_e32 v22, v22
	v_exp_f32_e32 v23, v23
	v_exp_f32_e32 v24, v24
	v_exp_f32_e32 v25, v25
	v_add_f32_e32 v18, 1.0, v18
	v_add_f32_e32 v19, 1.0, v19
	v_add_f32_e32 v20, 1.0, v20
	v_add_f32_e32 v21, 1.0, v21
	v_rcp_f32_e32 v18, v18
	v_rcp_f32_e32 v19, v19
	v_rcp_f32_e32 v20, v20
	v_rcp_f32_e32 v21, v21
	v_add_f32_e32 v22, 1.0, v22
	v_add_f32_e32 v23, 1.0, v23
	v_add_f32_e32 v24, 1.0, v24
	v_add_f32_e32 v25, 1.0, v25
	v_rcp_f32_e32 v22, v22
	v_rcp_f32_e32 v23, v23
	v_rcp_f32_e32 v24, v24
	v_rcp_f32_e32 v25, v25
	v_pk_mul_f32 v[18:19], v[18:19], s[30:31] op_sel_hi:[1,0]
	v_pk_mul_f32 v[20:21], v[20:21], s[30:31] op_sel_hi:[1,0]
	v_pk_mul_f32 v[22:23], v[22:23], s[30:31] op_sel_hi:[1,0]
	v_pk_mul_f32 v[24:25], v[24:25], s[30:31] op_sel_hi:[1,0]
	ds_write_b128 v97, v[18:21]
	ds_write_b128 v97, v[22:25] offset:16
	s_waitcnt lgkmcnt(0)
	s_barrier
	ds_read2st64_b32 v[178:179], v129 offset1:1
	ds_read2st64_b32 v[180:181], v129 offset0:2 offset1:3
	ds_read2st64_b32 v[182:183], v129 offset0:4 offset1:5
	ds_read2st64_b32 v[184:185], v129 offset0:6 offset1:7
	s_nop 0
	v_mov_b32_e32 v26, 0
	s_waitcnt lgkmcnt(3)
	v_add_f32_e32 v27, 0, v178
	v_add_f32_e32 v30, v27, v179
	s_nop 0
	ds_write2st64_b32 v129, v27, v30 offset1:1
	s_waitcnt lgkmcnt(3)
	v_add_f32_e32 v27, v30, v180
	v_add_f32_e32 v30, v27, v181
	s_nop 0
	ds_write2st64_b32 v129, v27, v30 offset0:2 offset1:3
	s_waitcnt lgkmcnt(1)
	v_add_f32_e32 v27, v30, v182
	v_add_f32_e32 v30, v27, v183
	s_nop 0
	ds_write2st64_b32 v129, v27, v30 offset0:4 offset1:5
	s_waitcnt lgkmcnt(1)
	v_add_f32_e32 v27, v30, v184
	v_add_f32_e32 v28, v27, v185
	v_mov_b32_e32 v29, v185
	ds_write2st64_b32 v129, v27, v28 offset0:6 offset1:7
	ds_write_b32 v98, v28
	v_mov_b32_e32 v27, 0
	s_waitcnt lgkmcnt(0)
	s_barrier
	s_and_saveexec_b64 s[0:1], s[48:49]
	s_cbranch_execz .LBB0_159
	ds_read_b32 v27, v99
	s_waitcnt lgkmcnt(0)
	v_add_f32_e32 v27, 0, v27

; __device__ __forceinline__ unsigned f2bf(float f) { return pk2(f, 0.f) & 0xffffu; }
; template <bool PA> ...
;     bf16* M = (bf16*)lds;
;     ...
;     bf16* w2T = MAT(13); bf16* a2T = MAT(14); float* wc = (float*)MAT(15); float* cst = wc + 64;
;     float* zbuf = (float*)MAT(0); float* abuf = zbuf + 4096;
;     float* cumb = (float*)MAT(10); float* segtot = cumb + 4096;
;     const int nch = slab == 0 ? 129 : 257, G = slab == 0 ? 4 : 8, nitems = 256, NCHA = nch;
;     const int lane = tid & 63, wave = tid >> 6, r16 = lane & 15, kq = lane >> 4, mt = wave >> 1, ntb = 2 * (wave & 1);
;     const int j = tid >> 3, part = tid & 7, c8 = part * 8;
;     const int tunit = ((j >> 3) + 1) * (4 * (j >> 3) + (j & 7)) + part; const bool tlow = part <= (j >> 3);
;     for (int item = blockIdx.x; item < nitems; item += gridDim.x) {
;         const int g = item % G, strm = item / G; const int p0 = g == 0 ? 0 : 1 + 32 * g, p1 = 33 + 32 * g;
;         const bool haveT = !PA;
;         const int d = strm & 1, head = (strm >> 1) & 15, sq = strm >> 5; const int seqbase = sq * 8256; const int hc8 = head * 64 + c8;
;         bf16* Op = d ? OBb : OFb;
;         const float* w0 = a->in[15] + d * 1024; const float* w2 = a->in[17] + (size_t)d * 64 * 1024; const float* a0 = a->in[18] + d * 1024; const float* a2 = a->in[20] + (size_t)d * 64 * 1024;
;         __syncthreads();
;         if (tid < 320) { const int wch = tid >> 6, cc = tid & 63; const float* src = wch == 0 ? w0 : (wch == 1 ? a0 : (wch == 2 ? a->in[23] : (wch == 3 ? a->in[24] : a->in[25]))); cst[tid] = src[head * 64 + cc]; }
;         for (int i = tid; i < 4096; i += 512) { const int l = i >> 6, cc = i & 63; w2T[cc * 72 + l] = (bf16)f2bf(w2[(size_t)l * 1024 + head * 64 + cc]); a2T[cc * 72 + l] = (bf16)f2bf(a2[(size_t)l * 1024 + head * 64 + cc]); }
;         f32x4_t Sacc[2], S2acc[2]; Sacc[0] = (f32x4_t){0.f, 0.f, 0.f, 0.f}; Sacc[1] = Sacc[0];
; #pragma unroll
;         for (int i = 0; i < 2; ++i)
; #pragma unroll
;             for (int e = 0; e < 4; ++e) S2acc[i][e] = (16 * mt + 4 * kq + e == 16 * (ntb + i) + r16) ? 1.f : 0.f;
.LBB0_190:
	s_andn2_b64 vcc, exec, s[0:1]
	s_cbranch_vccnz .LBB0_250
	v_readlane_b32 s0, v253, 2
	v_readlane_b32 s1, v253, 3
	s_andn2_b64 vcc, exec, s[0:1]
	s_cbranch_vccnz .LBB0_250
	v_ashrrev_i32_e32 v103, 6, v202
	v_writelane_b32 v255, s70, 18
	v_ashrrev_i32_e32 v104, 3, v202
	v_lshlrev_b32_e32 v0, 1, v103
	v_writelane_b32 v255, s71, 19
	v_and_b32_e32 v11, 2, v0
	v_and_b32_e32 v0, 7, v104
	v_lshl_add_u32 v0, v103, 2, v0
	v_readlane_b32 s12, v255, 5
	v_mad_u64_u32 v[2:3], s[8:9], v0, v103, v[0:1]
	v_readlane_b32 s13, v255, 6
	s_load_dwordx2 s[8:9], s[12:13], 0x78
	v_and_b32_e32 v9, 7, v203
	v_lshlrev_b32_e32 v0, 4, v9
	s_add_u32 s0, s6, 0x9a00000
	v_and_b32_e32 v5, 15, v203
	s_waitcnt lgkmcnt(0)
	v_writelane_b32 v255, s8, 32
	v_add_u32_e32 v4, 0, v0
	v_lshl_add_u64 v[6:7], s[6:7], 0, v[0:1]
	v_writelane_b32 v255, s9, 33
	s_load_dwordx4 s[8:11], s[12:13], 0x88
	s_load_dwordx2 s[38:39], s[12:13], 0xa0
	v_cmp_lt_u32_e64 s[12:13], 63, v202
	s_movk_i32 s15, 0x90
	s_addc_u32 s1, s7, 0
	v_writelane_b32 v255, s12, 20
	v_lshl_or_b32 v22, v11, 4, v5
	s_add_u32 s18, s6, 0xba80000
	v_writelane_b32 v255, s13, 21
	s_mov_b64 s[12:13], 0x730000
	v_lshl_add_u64 v[66:67], v[6:7], 0, s[12:13]
	v_mad_u64_u32 v[68:69], s[12:13], v104, s15, v[4:5]
	s_mov_b64 s[12:13], 0xb40000
	v_mul_u32_u24_e32 v23, 0x48, v22
	s_addc_u32 s19, s7, 0
	v_lshl_add_u64 v[70:71], v[6:7], 0, s[12:13]
	v_and_b32_e32 v21, 48, v203
	v_lshlrev_b32_e32 v23, 1, v23
	v_readlane_b32 s12, v254, 31
	s_add_u32 s22, s6, 0xdb00000
	v_and_b32_e32 v102, 63, v203
	v_add3_u32 v108, s12, v21, v23
	v_readlane_b32 s12, v254, 32
	s_addc_u32 s23, s7, 0
	v_bfe_u32 v3, v203, 4, 2
	v_lshlrev_b32_e32 v8, 2, v202
	v_and_b32_e32 v10, -16, v104
	v_lshlrev_b32_e32 v14, 2, v102
	v_add3_u32 v109, s12, v21, v23
	v_lshlrev_b32_e32 v24, 8, v104
	v_readlane_b32 s12, v254, 33
	s_cmp_eq_u32 s40, 0
	s_movk_i32 s2, 0x81
	v_readlane_b32 s20, v254, 26
	v_lshlrev_b32_e32 v12, 5, v9
	v_readlane_b32 s21, v254, 27
	v_lshlrev_b32_e32 v7, 3, v3
	v_add3_u32 v110, v4, v0, v24
	v_add_u32_e32 v113, s12, v8
	v_add_u32_e32 v114, s12, v14
	v_readlane_b32 s13, v254, 34
	v_lshlrev_b32_e32 v4, 1, v10
	v_readlane_b32 s12, v254, 28
	s_cselect_b32 s91, s2, 0x101
	s_movk_i32 s2, 0x140
	v_add_u32_e32 v106, s20, v8
	v_lshl_or_b32 v13, v3, 2, v10
	v_readlane_b32 s24, v254, 30
	v_bfi_b32 v6, -16, v104, v203
	v_add_u32_e32 v111, s20, v12
	v_add3_u32 v112, s21, v12, v24
	v_add_u32_e32 v115, s13, v12
	v_add_u32_e32 v8, s12, v4
	v_add_u32_e32 v10, 0x900, v23
	v_add3_u32 v126, s12, v21, v23
	v_add3_u32 v12, 0, v4, v7
	s_mov_b32 s12, 0xfc00
	v_cmp_gt_i32_e64 s[36:37], s2, v202
	s_movk_i32 s2, 0x1000
	v_lshlrev_b32_e32 v15, 1, v5
	v_mul_lo_u32 v6, v6, s15
	v_add_u32_e32 v3, 0, v21
	v_add3_u32 v120, v8, v7, v23
	v_add_u32_e32 v8, s24, v21
	v_add3_u32 v129, v12, v10, s12
	v_readlane_b32 s12, v254, 29
	s_mov_b32 s95, s40
	s_cselect_b32 s78, 4, 8
	v_cmp_gt_i32_e64 s[40:41], s2, v202
	s_add_i32 s2, 0, 0x12000
	v_add_u32_e32 v19, s21, v15
	v_add_u32_e32 v69, v3, v6
	v_mul_lo_u32 v25, v13, s15
	s_waitcnt vmcnt(0)
	v_lshlrev_b32_e32 v26, 5, v11
	v_add_u32_e32 v118, v3, v23
	v_add_u32_e32 v122, v8, v23
	v_add_u32_e32 v3, v3, v10
	v_add_u32_e32 v10, s12, v4
	v_add_u32_e32 v134, v8, v6
	v_cmp_eq_u32_e64 s[44:45], v13, v22
	v_or_b32_e32 v8, 1, v13
	v_add3_u32 v121, v19, v25, v26
	v_add3_u32 v130, v10, v7, v23
	v_add_u32_e32 v10, s2, v4
	v_add_u32_e32 v4, s24, v4
	v_cndmask_b32_e64 v136, 0, 1.0, s[44:45]
	v_cmp_eq_u32_e64 s[44:45], v8, v22
	v_or_b32_e32 v19, 2, v13
	v_add_u32_e32 v17, s24, v15
	v_add_u32_e32 v127, v12, v23
	v_add3_u32 v131, v10, v7, v23
	v_add3_u32 v132, s12, v21, v23
	v_add3_u32 v133, v4, v7, v23
	v_or_b32_e32 v7, 1, v11
	v_cndmask_b32_e64 v137, 0, 1.0, s[44:45]
	v_cmp_eq_u32_e64 s[44:45], v19, v22
	v_or_b32_e32 v23, 3, v13
	v_add3_u32 v117, v17, v25, v26
	v_lshl_or_b32 v17, v7, 4, v5
	v_cndmask_b32_e64 v138, 0, 1.0, s[44:45]
	v_cmp_eq_u32_e64 s[44:45], v23, v22
	v_add_u32_e32 v16, 0, v15
	v_add_u32_e32 v18, s2, v15
	v_cndmask_b32_e64 v139, 0, 1.0, s[44:45]
	v_cmp_eq_u32_e64 s[44:45], v13, v17
	v_add_u32_e32 v20, s21, v14
	v_add3_u32 v116, v16, v25, v26
	v_add3_u32 v119, v18, v25, v26
	v_add3_u32 v125, s2, v6, v21
	v_add3_u32 v128, s21, v6, v21
	v_lshlrev_b32_e32 v6, 6, v13
	v_cndmask_b32_e64 v140, 0, 1.0, s[44:45]
	v_cmp_eq_u32_e64 s[44:45], v8, v17
	v_lshlrev_b32_e32 v14, 6, v8
	v_lshlrev_b32_e32 v16, 6, v19
	v_lshlrev_b32_e32 v18, 6, v23
	v_or_b32_e32 v4, v17, v6
	v_cndmask_b32_e64 v141, 0, 1.0, s[44:45]
	v_cmp_eq_u32_e64 s[44:45], v19, v17
	v_or_b32_e32 v6, v22, v6
	v_or_b32_e32 v8, v14, v22
	v_or_b32_e32 v10, v16, v22
	v_or_b32_e32 v12, v18, v22
	v_cmp_lt_i32_e64 s[58:59], v22, v13
	v_cmp_gt_i32_e64 s[60:61], v22, v13
	v_cmp_lt_i32_e64 s[62:63], v22, v19
	v_cmp_lt_i32_e64 s[64:65], v22, v23
	v_lshlrev_b32_e32 v22, 6, v11
	v_cvt_f32_ubyte0_e32 v11, s78
	v_cndmask_b32_e64 v142, 0, 1.0, s[44:45]
	v_cmp_eq_u32_e64 s[44:45], v23, v17
	v_or_b32_e32 v14, v17, v14
	v_or_b32_e32 v16, v17, v16
	v_or_b32_e32 v18, v17, v18
	v_cmp_lt_i32_e64 s[66:67], v17, v13
	v_cmp_gt_i32_e64 s[68:69], v17, v13
	v_cmp_lt_i32_e64 s[70:71], v17, v19
	v_cmp_lt_i32_e64 s[72:73], v17, v23
	v_rcp_iflag_f32_e32 v17, v11
	v_lshlrev_b32_e32 v105, 3, v9
	v_cmp_le_i32_e32 vcc, v9, v103
	v_add_lshl_u32 v2, v2, v9, 3
	v_mul_u32_u24_e32 v9, 0x240, v9
	v_lshlrev_b32_e32 v24, 1, v104
	v_lshlrev_b32_e32 v9, 1, v9
	v_mul_f32_e32 v17, 0x4f7ffffe, v17
	v_add3_u32 v154, 0, v24, v9
	v_cvt_u32_f32_e32 v24, v17
	v_add_u32_e32 v9, s2, v25
	s_sub_i32 s2, 0, s78
	v_add_u32_e32 v123, 0xfc00, v3
	v_readfirstlane_b32 s12, v24
	s_mul_i32 s2, s2, s12
	v_add_u32_e32 v124, 0xfc40, v3
	v_ashrrev_i32_e32 v3, 31, v2
	v_add3_u32 v155, v9, v15, v26
	v_add_u32_e32 v9, 0, v25
	s_mul_hi_u32 s2, s12, s2
	v_lshlrev_b32_e32 v0, 11, v103
	v_lshl_add_u32 v21, v5, 2, s13
	v_ashrrev_i32_e32 v5, 31, v4
	s_waitcnt vmcnt(47)
; __device__ __forceinline__ unsigned f2bf(float f) { return pk2(f, 0.f) & 0xffffu; }
; template <bool PA> ...
;     ...
;     const int lane = tid & 63, wave = tid >> 6, r16 = lane & 15, kq = lane >> 4, mt = wave >> 1, ntb = 2 * (wave & 1);
;     const int j = tid >> 3, part = tid & 7, c8 = part * 8;
;     const int tunit = ((j >> 3) + 1) * (4 * (j >> 3) + (j & 7)) + part; const bool tlow = part <= (j >> 3);
;     for (int item = blockIdx.x; item < nitems; item += gridDim.x) {
;         const int g = item % G, strm = item / G; const int p0 = g == 0 ? 0 : 1 + 32 * g, p1 = 33 + 32 * g;
;         const bool haveT = !PA;
;         const int d = strm & 1, head = (strm >> 1) & 15, sq = strm >> 5; const int seqbase = sq * 8256; const int hc8 = head * 64 + c8;
;         bf16* Op = d ? OBb : OFb;
;         const float* w0 = a->in[15] + d * 1024; const float* w2 = a->in[17] + (size_t)d * 64 * 1024; const float* a0 = a->in[18] + d * 1024; const float* a2 = a->in[20] + (size_t)d * 64 * 1024;
;         __syncthreads();
;         if (tid < 320) { const int wch = tid >> 6, cc = tid & 63; const float* src = wch == 0 ? w0 : (wch == 1 ? a0 : (wch == 2 ? a->in[23] : (wch == 3 ? a->in[24] : a->in[25]))); cst[tid] = src[head * 64 + cc]; }
;         for (int i = tid; i < 4096; i += 512) { const int l = i >> 6, cc = i & 63; w2T[cc * 72 + l] = (bf16)f2bf(w2[(size_t)l * 1024 + head * 64 + cc]); a2T[cc * 72 + l] = (bf16)f2bf(a2[(size_t)l * 1024 + head * 64 + cc]); }
;         f32x4_t Sacc[2], S2acc[2]; Sacc[0] = (f32x4_t){0.f, 0.f, 0.f, 0.f}; Sacc[1] = Sacc[0];
; #pragma unroll
;         for (int i = 0; i < 2; ++i)
; #pragma unroll
;             for (int e = 0; e < 4; ++e) S2acc[i][e] = (16 * mt + 4 * kq + e == 16 * (ntb + i) + r16) ? 1.f : 0.f;
	v_add3_u32 v156, v9, v15, v26
	v_lshlrev_b32_e32 v23, 6, v7
	v_ashrrev_i32_e32 v7, 31, v6
	v_ashrrev_i32_e32 v9, 31, v8
	v_ashrrev_i32_e32 v11, 31, v10
	v_ashrrev_i32_e32 v13, 31, v12
	v_ashrrev_i32_e32 v15, 31, v14
	v_ashrrev_i32_e32 v17, 31, v16
	v_ashrrev_i32_e32 v19, 31, v18
	s_add_i32 s2, s12, s2
	v_lshl_add_u64 v[2:3], v[2:3], 1, s[6:7]
	s_mov_b64 s[12:13], 0x2000000
	v_sub_u32_e32 v107, 63, v104
	v_cmp_eq_u32_e64 s[42:43], 63, v104
	v_mul_u32_u24_e32 v135, 0x48, v102
	v_cndmask_b32_e64 v143, 0, 1.0, s[44:45]
	v_lshl_add_u32 v144, v6, 2, 0
	v_lshl_add_u32 v145, v8, 2, 0
	v_lshl_add_u32 v148, v10, 2, 0
	v_lshl_add_u32 v149, v12, 2, 0
	v_lshl_add_u32 v150, v4, 2, 0
	v_lshl_add_u32 v151, v14, 2, 0
	v_lshl_add_u32 v152, v16, 2, 0
	v_lshl_add_u32 v153, v18, 2, 0
	v_cmp_lt_i32_e64 s[44:45], 0, v103
	v_cmp_lt_i32_e64 s[46:47], 1, v103
	v_cmp_lt_i32_e64 s[48:49], 2, v103
	v_cmp_lt_i32_e64 s[50:51], 3, v103
	v_cmp_lt_i32_e64 s[52:53], 4, v103
	v_cmp_lt_i32_e64 s[54:55], 5, v103
	v_cmp_lt_i32_e64 s[56:57], 6, v103
	v_lshl_add_u64 v[72:73], v[2:3], 0, s[12:13]
	s_add_i32 s79, s91, -1
	s_waitcnt vmcnt(46)
	v_add_u32_e32 v157, v21, v22
	v_add_u32_e32 v158, v21, v23
	v_lshlrev_b64 v[74:75], 2, v[6:7]
	v_lshlrev_b64 v[76:77], 2, v[8:9]
	v_lshlrev_b64 v[78:79], 2, v[10:11]
	v_lshlrev_b64 v[80:81], 2, v[12:13]
	v_lshlrev_b64 v[82:83], 2, v[4:5]
	v_lshlrev_b64 v[84:85], 2, v[14:15]
	v_lshlrev_b64 v[86:87], 2, v[16:17]
	v_lshlrev_b64 v[88:89], 2, v[18:19]
	s_waitcnt vmcnt(45)
; template <bool PA> ...
;     bf16* M = (bf16*)lds;
;     ...
;     bf16* w2T = MAT(13); bf16* a2T = MAT(14); float* wc = (float*)MAT(15); float* cst = wc + 64;
;     float* zbuf = (float*)MAT(0); float* abuf = zbuf + 4096;
;     float* cumb = (float*)MAT(10); float* segtot = cumb + 4096;
;     const int nch = slab == 0 ? 129 : 257, G = slab == 0 ? 4 : 8, nitems = 256, NCHA = nch;
;     const int lane = tid & 63, wave = tid >> 6, r16 = lane & 15, kq = lane >> 4, mt = wave >> 1, ntb = 2 * (wave & 1);
;     const int j = tid >> 3, part = tid & 7, c8 = part * 8;
;     const int tunit = ((j >> 3) + 1) * (4 * (j >> 3) + (j & 7)) + part; const bool tlow = part <= (j >> 3);
	v_add_u32_e32 v159, v20, v0
	v_readfirstlane_b32 s15, v202
	v_mov_b32_e32 v185, v154
	s_mov_b32 s12, 0x0
	s_mov_b32 s13, 0x55555555
	s_bitcmp1_b32 s15, 6
	s_cmov_b32 s12, 0x55555555
	s_cmov_b32 s13, 0x0
	v_cndmask_b32_e64 v201, 0, 16, s[12:13]
	s_mov_b32 s12, 0x0
	s_mov_b32 s13, 0xaaaaaaaa
	s_bitcmp1_b32 s15, 6
	s_cmov_b32 s12, 0xaaaaaaaa
	s_cmov_b32 s13, 0x0
	v_cndmask_b32_e64 v252, 0, 16, s[12:13]
	v_sub_u32_e32 v201, v201, v252
	v_add_u32_e32 v68, v68, v201
	s_mov_b32 s12, 0xff0
	s_mov_b32 s13, 0xff0
	v_cndmask_b32_e64 v201, 0, 16, s[12:13]
	s_mov_b32 s12, 0xff00000
	s_mov_b32 s13, 0xff00000
	v_cndmask_b32_e64 v252, 0, 16, s[12:13]
	v_sub_u32_e32 v201, v201, v252
	v_add_u32_e32 v69, v69, v201
	s_mov_b32 s12, 0xff0000
	s_mov_b32 s13, 0xff
	v_cndmask_b32_e64 v201, 0, 16, s[12:13]
	s_mov_b32 s12, 0xff000000
	s_mov_b32 s13, 0xff00
	v_cndmask_b32_e64 v252, 0, 16, s[12:13]
	v_sub_u32_e32 v201, v201, v252
	v_add_u32_e32 v116, v116, v201
	s_mov_b32 s12, 0xff0000
	s_mov_b32 s13, 0xff
	v_cndmask_b32_e64 v201, 0, 16, s[12:13]
	s_mov_b32 s12, 0xff000000
	s_mov_b32 s13, 0xff00
	v_cndmask_b32_e64 v252, 0, 16, s[12:13]
	v_sub_u32_e32 v201, v201, v252
	v_add_u32_e32 v117, v117, v201
	s_mov_b32 s12, 0xff0
	s_mov_b32 s13, 0xff0
	v_cndmask_b32_e64 v201, 0, 16, s[12:13]
	s_mov_b32 s12, 0xff00000
	s_mov_b32 s13, 0xff00000
	v_cndmask_b32_e64 v252, 0, 16, s[12:13]
	v_sub_u32_e32 v201, v201, v252
	v_add_u32_e32 v118, v118, v201
	s_mov_b32 s12, 0xff0000
	s_mov_b32 s13, 0xff
	v_cndmask_b32_e64 v201, 0, 16, s[12:13]
	s_mov_b32 s12, 0xff000000
	s_mov_b32 s13, 0xff00
	v_cndmask_b32_e64 v252, 0, 16, s[12:13]
	v_sub_u32_e32 v201, v201, v252
	v_add_u32_e32 v119, v119, v201
	s_mov_b32 s12, 0xff00ff0
	s_mov_b32 s13, 0x0
	v_cndmask_b32_e64 v201, 0, 16, s[12:13]
	s_mov_b32 s12, 0x0
	s_mov_b32 s13, 0xff00ff0
	v_cndmask_b32_e64 v252, 0, 16, s[12:13]
	v_sub_u32_e32 v201, v201, v252
	v_add_u32_e32 v120, v120, v201
	s_mov_b32 s12, 0xff0000
	s_mov_b32 s13, 0xff
	v_cndmask_b32_e64 v201, 0, 16, s[12:13]
	s_mov_b32 s12, 0xff000000
	s_mov_b32 s13, 0xff00
	v_cndmask_b32_e64 v252, 0, 16, s[12:13]
	v_sub_u32_e32 v201, v201, v252
	v_add_u32_e32 v121, v121, v201
	s_mov_b32 s12, 0xff0
	s_mov_b32 s13, 0xff0
	v_cndmask_b32_e64 v201, 0, 16, s[12:13]
	s_mov_b32 s12, 0xff00000
	s_mov_b32 s13, 0xff00000
	v_cndmask_b32_e64 v252, 0, 16, s[12:13]
	v_sub_u32_e32 v201, v201, v252
	v_add_u32_e32 v122, v122, v201
	s_mov_b32 s12, 0xff0
	s_mov_b32 s13, 0xff0
	v_cndmask_b32_e64 v201, 0, 16, s[12:13]
	s_mov_b32 s12, 0xff00000
	s_mov_b32 s13, 0xff00000
	v_cndmask_b32_e64 v252, 0, 16, s[12:13]
	v_sub_u32_e32 v201, v201, v252
	v_add_u32_e32 v123, v123, v201
	s_mov_b32 s12, 0xff0
	s_mov_b32 s13, 0xff0
	v_cndmask_b32_e64 v201, 0, 16, s[12:13]
	s_mov_b32 s12, 0xff00000
	s_mov_b32 s13, 0xff00000
	v_cndmask_b32_e64 v252, 0, 16, s[12:13]
	v_sub_u32_e32 v201, v201, v252
	v_add_u32_e32 v124, v124, v201
	s_mov_b32 s12, 0xff0
	s_mov_b32 s13, 0xff0
	v_cndmask_b32_e64 v201, 0, 16, s[12:13]
	s_mov_b32 s12, 0xff00000
	s_mov_b32 s13, 0xff00000
	v_cndmask_b32_e64 v252, 0, 16, s[12:13]
	v_sub_u32_e32 v201, v201, v252
	v_add_u32_e32 v125, v125, v201
	s_mov_b32 s12, 0xff0
	s_mov_b32 s13, 0xff0
	v_cndmask_b32_e64 v201, 0, 16, s[12:13]
	s_mov_b32 s12, 0xff00000
	s_mov_b32 s13, 0xff00000
	v_cndmask_b32_e64 v252, 0, 16, s[12:13]
	v_sub_u32_e32 v201, v201, v252
	v_add_u32_e32 v126, v126, v201
	s_mov_b32 s12, 0xff00ff0
	s_mov_b32 s13, 0x0
	v_cndmask_b32_e64 v201, 0, 16, s[12:13]
	s_mov_b32 s12, 0x0
	s_mov_b32 s13, 0xff00ff0
	v_cndmask_b32_e64 v252, 0, 16, s[12:13]
	v_sub_u32_e32 v201, v201, v252
	v_add_u32_e32 v127, v127, v201
	s_mov_b32 s12, 0xff0
	s_mov_b32 s13, 0xff0
	v_cndmask_b32_e64 v201, 0, 16, s[12:13]
	s_mov_b32 s12, 0xff00000
	s_mov_b32 s13, 0xff00000
	v_cndmask_b32_e64 v252, 0, 16, s[12:13]
	v_sub_u32_e32 v201, v201, v252
	v_add_u32_e32 v128, v128, v201
	s_mov_b32 s12, 0xff00ff0
	s_mov_b32 s13, 0x0
	v_cndmask_b32_e64 v201, 0, 16, s[12:13]
	s_mov_b32 s12, 0x0
	s_mov_b32 s13, 0xff00ff0
	v_cndmask_b32_e64 v252, 0, 16, s[12:13]
	v_sub_u32_e32 v201, v201, v252
	v_add_u32_e32 v129, v129, v201
	s_mov_b32 s12, 0xff00ff0
	s_mov_b32 s13, 0x0
	v_cndmask_b32_e64 v201, 0, 16, s[12:13]
	s_mov_b32 s12, 0x0
	s_mov_b32 s13, 0xff00ff0
	v_cndmask_b32_e64 v252, 0, 16, s[12:13]
	v_sub_u32_e32 v201, v201, v252
	v_add_u32_e32 v130, v130, v201
	s_mov_b32 s12, 0xff00ff0
	s_mov_b32 s13, 0x0
	v_cndmask_b32_e64 v201, 0, 16, s[12:13]
	s_mov_b32 s12, 0x0
	s_mov_b32 s13, 0xff00ff0
	v_cndmask_b32_e64 v252, 0, 16, s[12:13]
	v_sub_u32_e32 v201, v201, v252
	v_add_u32_e32 v131, v131, v201
	s_mov_b32 s12, 0xff0
	s_mov_b32 s13, 0xff0
	v_cndmask_b32_e64 v201, 0, 16, s[12:13]
	s_mov_b32 s12, 0xff00000
	s_mov_b32 s13, 0xff00000
	v_cndmask_b32_e64 v252, 0, 16, s[12:13]
	v_sub_u32_e32 v201, v201, v252
	v_add_u32_e32 v132, v132, v201
	s_mov_b32 s12, 0xff00ff0
	s_mov_b32 s13, 0x0
	v_cndmask_b32_e64 v201, 0, 16, s[12:13]
	s_mov_b32 s12, 0x0
	s_mov_b32 s13, 0xff00ff0
	v_cndmask_b32_e64 v252, 0, 16, s[12:13]
	v_sub_u32_e32 v201, v201, v252
	v_add_u32_e32 v133, v133, v201
	s_mov_b32 s12, 0xff0
	s_mov_b32 s13, 0xff0
	v_cndmask_b32_e64 v201, 0, 16, s[12:13]
	s_mov_b32 s12, 0xff00000
	s_mov_b32 s13, 0xff00000
	v_cndmask_b32_e64 v252, 0, 16, s[12:13]
	v_sub_u32_e32 v201, v201, v252
	v_add_u32_e32 v134, v134, v201
	s_mov_b32 s12, 0xaaaaaaaa
	s_mov_b32 s13, 0xaaaaaaaa
	s_bitcmp1_b32 s15, 6
	s_cmov_b32 s12, 0x0
	s_cmov_b32 s13, 0x0
	v_cndmask_b32_e64 v201, 0, 16, s[12:13]
	s_mov_b32 s12, 0x0
	s_mov_b32 s13, 0x0
	s_bitcmp1_b32 s15, 6
	s_cmov_b32 s12, 0xaaaaaaaa
	s_cmov_b32 s13, 0xaaaaaaaa
	v_cndmask_b32_e64 v252, 0, 16, s[12:13]
	v_sub_u32_e32 v201, v201, v252
	v_add_u32_e32 v154, v154, v201
	s_mov_b32 s12, 0x55555555
	s_mov_b32 s13, 0x55555555
	s_bitcmp1_b32 s15, 6
	s_cmov_b32 s12, 0x0
	s_cmov_b32 s13, 0x0
	v_cndmask_b32_e64 v201, 0, 16, s[12:13]
	s_mov_b32 s12, 0x0
	s_mov_b32 s13, 0x0
	s_bitcmp1_b32 s15, 6
	s_cmov_b32 s12, 0x55555555
	s_cmov_b32 s13, 0x55555555
	v_cndmask_b32_e64 v252, 0, 16, s[12:13]
	v_sub_u32_e32 v201, v201, v252
	v_add_u32_e32 v185, v185, v201
	s_mov_b32 s12, 0xff0000
	s_mov_b32 s13, 0xff
	v_cndmask_b32_e64 v201, 0, 16, s[12:13]
	s_mov_b32 s12, 0xff000000
	s_mov_b32 s13, 0xff00
	v_cndmask_b32_e64 v252, 0, 16, s[12:13]
	v_sub_u32_e32 v201, v201, v252
	v_add_u32_e32 v155, v155, v201
	s_mov_b32 s12, 0xff0000
	s_mov_b32 s13, 0xff
	v_cndmask_b32_e64 v201, 0, 16, s[12:13]
	s_mov_b32 s12, 0xff000000
	s_mov_b32 s13, 0xff00
	v_cndmask_b32_e64 v252, 0, 16, s[12:13]
	v_sub_u32_e32 v201, v201, v252
	v_add_u32_e32 v156, v156, v201
	s_mov_b32 s82, s96
	s_branch .LBB0_194

; template <bool PA> ...
;     ...
;             float rv[8], kk[8], av[8], kd[8], lw[8]; u32x4_t tld = (u32x4_t){0u, 0u, 0u, 0u}, vraw = (u32x4_t){0u, 0u, 0u, 0u};
;             {
;                 const size_t row = cbase + (d ? 63 - j : j);
;                 asm volatile("" ::: "memory");
;                 if (haveT && tlow) tld = *(const u32x4_t*)(tbuf + ((size_t)strm * NCHA + p) * 2304 + tunit * 8);
;                 *(u32x4_t*)(MAT(4) + j * 72 + c8) = *(const u32x4_t*)(HWb + row * 128 + d * 64 + c8);
;                 *(u32x4_t*)(MAT(5) + j * 72 + c8) = *(const u32x4_t*)(HAb + row * 128 + d * 64 + c8);
;                 const u32x4_t rw = *(const u32x4_t*)(Rb + row * 1024 + hc8), kw = *(const u32x4_t*)(Kb + row * 1024 + hc8), vw = *(const u32x4_t*)(Vb + row * 1024 + hc8);
;                 __syncthreads();
;                 { f32x4_t za[2], xa[2]; za[0] = (f32x4_t){0.f, 0.f, 0.f, 0.f}; za[1] = za[0]; xa[0] = za[0]; xa[1] = za[0];
;                   mm2(za, MAT(4), w2T, mt, ntb, r16, kq); mm2(xa, MAT(5), a2T, mt, ntb, r16, kq);
; #pragma unroll
;                   for (int i = 0; i < 2; ++i)
; #pragma unroll
;                       for (int e = 0; e < 4; ++e) { zbuf[(16 * mt + 4 * kq + e) * 64 + 16 * (ntb + i) + r16] = za[i][e]; abuf[(16 * mt + 4 * kq + e) * 64 + 16 * (ntb + i) + r16] = xa[i][e]; } }
;                 __syncthreads();
;                 const unsigned rwa[4] = {rw.x, rw.y, rw.z, rw.w}, kwa[4] = {kw.x, kw.y, kw.z, kw.w};
;                 float kv[8], z[8], aa[8];
; #pragma unroll
;                 for (int q = 0; q < 4; ++q) { rv[2 * q] = __uint_as_float(rwa[q] << 16); rv[2 * q + 1] = __uint_as_float(rwa[q] & 0xffff0000u); kv[2 * q] = __uint_as_float(kwa[q] << 16); kv[2 * q + 1] = __uint_as_float(kwa[q] & 0xffff0000u);
;                 }
;                 vraw = vw;
;                 { const f32x4_t z0 = *(const f32x4_t*)(zbuf + j * 64 + c8), z1 = *(const f32x4_t*)(zbuf + j * 64 + c8 + 4), x0 = *(const f32x4_t*)(abuf + j * 64 + c8), x1 = *(const f32x4_t*)(abuf + j * 64 + c8 + 4);
; #pragma unroll
;                   for (int e = 0; e < 4; ++e) { z[e] = cst[c8 + e] + z0[e]; z[4 + e] = cst[c8 + 4 + e] + z1[e]; aa[e] = cst[64 + c8 + e] + x0[e]; aa[4 + e] = cst[64 + c8 + 4 + e] + x1[e]; } }
;                 asm volatile("" ::: "memory");
;                 float ss = 0.f, bsum = 0.f;
; #pragma unroll
.LBB0_213:
	s_waitcnt vmcnt(1)
	ds_write_b128 v68, v[232:235] offset:36864
	ds_write_b128 v68, v[236:239] offset:46080
	v_mov_b32_e32 v22, v240
	v_mov_b32_e32 v23, v241
	v_mov_b32_e32 v24, v242
	v_mov_b32_e32 v25, v243
	v_mov_b32_e32 v26, v244
	v_mov_b32_e32 v27, v245
	v_mov_b32_e32 v28, v246
	v_mov_b32_e32 v29, v247
	v_mov_b32_e32 v18, v248
	v_mov_b32_e32 v19, v249
	v_mov_b32_e32 v20, v250
	v_mov_b32_e32 v21, v251
	s_and_b64 s[12:13], s[74:75], exec
	s_cselect_b32 s12, s20, s24
	s_cselect_b32 s13, 64, 0xffffffc0
	v_lshl_add_u32 v226, s12, 6, v160
	s_add_i32 s12, s20, 1
	s_cmp_lt_i32 s12, s21
	s_cselect_b32 s13, s13, 0
	v_add_u32_e32 v226, s13, v226
	v_ashrrev_i32_e32 v227, 31, v226
	v_lshlrev_b64 v[224:225], 8, v[226:227]
	v_lshl_add_u64 v[222:223], v[90:91], 0, v[224:225]
	global_load_dwordx4 v[232:235], v[222:223], off
	v_lshl_add_u64 v[222:223], v[92:93], 0, v[224:225]
	global_load_dwordx4 v[236:239], v[222:223], off
	v_lshlrev_b64 v[224:225], 11, v[226:227]
	v_lshl_add_u64 v[222:223], v[94:95], 0, v[224:225]
	global_load_dwordx4 v[240:243], v[222:223], off
	v_lshl_add_u64 v[222:223], v[96:97], 0, v[224:225]
	global_load_dwordx4 v[244:247], v[222:223], off
	v_lshl_add_u64 v[222:223], v[98:99], 0, v[224:225]
	global_load_dwordx4 v[248:251], v[222:223], off
	s_waitcnt lgkmcnt(0)
	s_barrier
	ds_read_b128 v[186:189], v69 offset:36864
	ds_read_b128 v[190:193], v108
	ds_read_b128 v[204:207], v108 offset:2304
	ds_read_b128 v[208:211], v69 offset:36928
	ds_read_b128 v[212:215], v108 offset:64
	ds_read_b128 v[216:219], v108 offset:2368
	ds_read_b128 v[220:223], v69 offset:46080
	ds_read_b128 v[224:227], v109
	s_nop 0
	s_nop 0
	s_nop 0
	s_waitcnt lgkmcnt(6)
	v_mfma_f32_16x16x32_bf16 v[34:37], v[186:189], v[190:193], 0
	ds_read_b128 v[190:193], v109 offset:2304
	s_nop 0
	v_lshlrev_b32_e32 v161, 16, v26
	s_waitcnt lgkmcnt(6)
	v_mfma_f32_16x16x32_bf16 v[30:33], v[186:189], v[204:207], 0
	ds_read_b128 v[186:189], v69 offset:46144
	ds_read_b128 v[204:207], v109 offset:64
	s_nop 0
	s_nop 0
	v_and_b32_e32 v163, 0xffff0000, v26
	v_lshlrev_b32_e32 v165, 16, v27
	s_waitcnt lgkmcnt(6)
	v_mfma_f32_16x16x32_bf16 v[34:37], v[208:211], v[212:215], v[34:37]
	ds_read_b128 v[212:215], v109 offset:2368
	s_nop 0
	v_and_b32_e32 v167, 0xffff0000, v27
	v_lshlrev_b32_e32 v169, 16, v28
	s_waitcnt lgkmcnt(6)
	v_mfma_f32_16x16x32_bf16 v[30:33], v[208:211], v[216:219], v[30:33]
	s_nop 0
	s_nop 0
	s_nop 0
	v_and_b32_e32 v171, 0xffff0000, v28
	s_waitcnt lgkmcnt(4)
	v_mfma_f32_16x16x32_bf16 v[42:45], v[220:223], v[224:227], 0
	v_lshlrev_b32_e32 v173, 16, v29
	v_and_b32_e32 v175, 0xffff0000, v29
	s_waitcnt lgkmcnt(3)
	v_mfma_f32_16x16x32_bf16 v[38:41], v[220:223], v[190:193], 0
	s_nop 0
	s_nop 0
	s_waitcnt lgkmcnt(1)
	v_mfma_f32_16x16x32_bf16 v[42:45], v[186:189], v[204:207], v[42:45]
	s_nop 0
	s_waitcnt lgkmcnt(0)
	v_mfma_f32_16x16x32_bf16 v[38:41], v[186:189], v[212:215], v[38:41]
	s_nop 4
	ds_write2st64_b32 v144, v34, v42 offset1:64
	ds_write2st64_b32 v145, v35, v43 offset1:64
	ds_write2st64_b32 v148, v36, v44 offset1:64
	ds_write2st64_b32 v149, v37, v45 offset1:64
	ds_write2st64_b32 v150, v30, v38 offset1:64
	ds_write2st64_b32 v151, v31, v39 offset1:64
	ds_write2st64_b32 v152, v32, v40 offset1:64
	ds_write2st64_b32 v153, v33, v41 offset1:64
	s_waitcnt lgkmcnt(0)
	s_barrier
	ds_read_b128 v[186:189], v110
	ds_read_b128 v[190:193], v110 offset:16
	ds_read_b128 v[204:207], v111
	ds_read_b128 v[208:211], v111 offset:16
	ds_read_b128 v[212:215], v111 offset:512
	ds_read_b128 v[216:219], v111 offset:528
	s_nop 0
	s_nop 0
	ds_read_b128 v[26:29], v110 offset:16384
	ds_read_b128 v[30:33], v110 offset:16400
	s_nop 0
	s_nop 0
	ds_read_b128 v[34:37], v111 offset:256
	ds_read_b128 v[38:41], v111 offset:272
	s_waitcnt lgkmcnt(2)
	v_add_f32_e32 v42, v186, v204
	s_waitcnt lgkmcnt(2)
	v_add_f32_e32 v50, v190, v208
	v_add_f32_e32 v46, v187, v205
	v_add_f32_e32 v54, v191, v209
	v_add_f32_e32 v49, v188, v206
	v_add_f32_e32 v57, v192, v210
	v_add_f32_e32 v48, v189, v207
	v_add_f32_e32 v56, v193, v211
	s_nop 0
	s_nop 0
	v_and_b32_e32 v45, 64, v198
	v_xor_b32_e32 v44, 1, v198
	v_add_u32_e32 v45, 64, v45
	s_waitcnt lgkmcnt(0)
	v_mul_f32_e32 v164, v213, v163
	v_mul_f32_e32 v162, v212, v161
	v_mul_f32_e32 v43, v164, v164
	v_fmac_f32_e32 v43, v162, v162
	v_mul_f32_e32 v166, v214, v165
	v_fmac_f32_e32 v43, v166, v166
	v_mul_f32_e32 v168, v215, v167
	v_mov_b32_e32 v61, v215
	v_fmac_f32_e32 v43, v168, v168
	s_waitcnt lgkmcnt(0)
	v_mul_f32_e32 v170, v216, v169
	v_fmac_f32_e32 v43, v170, v170
	v_mul_f32_e32 v172, v217, v171
	v_fmac_f32_e32 v43, v172, v172
	v_mul_f32_e32 v174, v218, v173
	v_cmp_lt_i32_e64 s[76:77], v44, v45
	v_fmac_f32_e32 v43, v174, v174
	v_mul_f32_e32 v176, v219, v175
	v_mov_b32_e32 v62, v216
	v_mov_b32_e32 v63, v217
	v_mov_b32_e32 v64, v218
	v_mov_b32_e32 v65, v219
	v_cndmask_b32_e64 v44, v198, v44, s[76:77]
	v_fmac_f32_e32 v43, v176, v176
	v_lshlrev_b32_e32 v44, 2, v44
	ds_bpermute_b32 v44, v44, v43
	v_mul_f32_e32 v42, 0xbfb8aa3b, v42
	v_mul_f32_e32 v46, 0xbfb8aa3b, v46
	v_exp_f32_e32 v42, v42
	v_exp_f32_e32 v46, v46
	v_mul_f32_e32 v50, 0xbfb8aa3b, v50
	v_mul_f32_e32 v54, 0xbfb8aa3b, v54
	s_waitcnt lgkmcnt(0)
	v_add_f32_e32 v43, v43, v44
	v_xor_b32_e32 v44, 2, v198
	v_exp_f32_e32 v50, v50
	v_exp_f32_e32 v54, v54
	v_cmp_lt_i32_e64 s[76:77], v44, v45
	v_mul_f32_e32 v49, 0xbfb8aa3b, v49
	v_mul_f32_e32 v48, 0xbfb8aa3b, v48
	v_cndmask_b32_e64 v44, v198, v44, s[76:77]
	v_lshlrev_b32_e32 v44, 2, v44
	v_add_f32_e32 v42, 1.0, v42
	v_add_f32_e32 v46, 1.0, v46
	v_exp_f32_e32 v49, v49
	v_exp_f32_e32 v48, v48
	v_mul_f32_e32 v57, 0xbfb8aa3b, v57
	v_mul_f32_e32 v56, 0xbfb8aa3b, v56
	ds_bpermute_b32 v44, v44, v43
	v_rcp_f32_e32 v52, v42
	v_rcp_f32_e32 v53, v46
	v_add_f32_e32 v50, 1.0, v50
	v_add_f32_e32 v54, 1.0, v54
	v_exp_f32_e32 v57, v57
	v_exp_f32_e32 v56, v56
	v_rcp_f32_e32 v58, v50
	v_rcp_f32_e32 v59, v54
	v_add_f32_e32 v49, 1.0, v49
	v_add_f32_e32 v48, 1.0, v48
	v_pk_mul_f32 v[46:47], v[52:53], s[30:31] op_sel_hi:[1,0]
	v_rcp_f32_e32 v52, v49
	v_rcp_f32_e32 v53, v48
	v_add_f32_e32 v57, 1.0, v57
	v_add_f32_e32 v56, 1.0, v56
	s_waitcnt lgkmcnt(0)
	v_add_f32_e32 v146, v43, v44
	v_xor_b32_e32 v43, 4, v198
	v_pk_mul_f32 v[54:55], v[58:59], s[30:31] op_sel_hi:[1,0]
	v_rcp_f32_e32 v58, v57
	v_rcp_f32_e32 v59, v56
	v_cmp_lt_i32_e64 s[76:77], v43, v45
	v_pk_mul_f32 v[48:49], v[52:53], s[30:31] op_sel_hi:[1,0]
	ds_read_b128 v[50:53], v111 offset:784
	v_cndmask_b32_e64 v43, v198, v43, s[76:77]
	v_lshlrev_b32_e32 v43, 2, v43
	ds_bpermute_b32 v147, v43, v146
	ds_read_b128 v[42:45], v111 offset:768
	v_pk_mul_f32 v[56:57], v[58:59], s[30:31] op_sel_hi:[1,0]
	ds_write_b128 v112, v[46:49]
	ds_write_b128 v112, v[54:57] offset:16
	s_waitcnt lgkmcnt(0)
	s_barrier
; template <bool PA> ...
;     ...
;             __syncthreads();
;             { const int c = tid & 63, sg = tid >> 6; float run = 0.f;
; #pragma unroll
;               for (int i = 0; i < 8; ++i) { run += cumb[(8 * sg + i) * 64 + c]; cumb[(8 * sg + i) * 64 + c] = run; }
;               segtot[sg * 64 + c] = run; }
;             __syncthreads();
;             { const int c = tid & 63, sg = tid >> 6; float off = 0.f;
; #pragma unroll
;               for (int s = 0; s < 7; ++s) off += (s < sg) ? segtot[s * 64 + c] : 0.f;
; #pragma unroll
;               for (int i = 0; i < 8; ++i) cumb[(8 * sg + i) * 64 + c] += off; }
;             __syncthreads();
;             {
;                 const f32x4_t c0 = *(const f32x4_t*)(cumb + j * 64 + c8), c1 = *(const f32x4_t*)(cumb + j * 64 + c8 + 4);
;                 float ah[8], bh[8], kh[8], rh[8];
; #pragma unroll
;                 for (int e = 0; e < 8; ++e) { const float cu = e < 4 ? c0[e & 3] : c1[e & 3]; const float Wt = __expf(cu), iW = __expf(-cu), Wm1 = __expf(cu - lw[e]);
;                     ah[e] = kk[e] * Wm1; bh[e] = -(kk[e] * av[e]) * iW; kh[e] = kd[e] * iW; rh[e] = rv[e] * Wt;
;                     if (j == 63) wc[c8 + e] = Wt; }
	ds_read2st64_b32 v[186:187], v159 offset1:1
	ds_read2st64_b32 v[188:189], v159 offset0:2 offset1:3
	ds_read2st64_b32 v[190:191], v159 offset0:4 offset1:5
	ds_read2st64_b32 v[192:193], v159 offset0:6 offset1:7
	s_nop 0
	s_waitcnt lgkmcnt(3)
	v_add_f32_e32 v58, 0, v186
	v_add_f32_e32 v60, v58, v187
	ds_write2st64_b32 v159, v58, v60 offset1:1
	s_nop 0
	s_waitcnt lgkmcnt(0)
	v_add_f32_e32 v58, v60, v188
	v_add_f32_e32 v60, v58, v189
	ds_write2st64_b32 v159, v58, v60 offset0:2 offset1:3
	s_nop 0
	s_waitcnt lgkmcnt(0)
	v_add_f32_e32 v58, v60, v190
	v_add_f32_e32 v60, v58, v191
	ds_write2st64_b32 v159, v58, v60 offset0:4 offset1:5
	s_nop 0
	s_waitcnt lgkmcnt(0)
	v_add_f32_e32 v58, v60, v192
	v_add_f32_e32 v59, v58, v193
	ds_write2st64_b32 v159, v58, v59 offset0:6 offset1:7
	ds_write_b32 v113, v59
	v_mov_b32_e32 v58, 0
	s_waitcnt lgkmcnt(0)
	s_barrier
	s_and_saveexec_b64 s[12:13], s[44:45]
	s_cbranch_execz .LBB0_215
	ds_read_b32 v58, v114
	s_waitcnt lgkmcnt(0)
	v_add_f32_e32 v58, 0, v58
.LBB0_215:
	s_or_b64 exec, exec, s[12:13]
	v_mov_b32_e32 v59, 0
	v_mov_b32_e32 v60, 0
	s_and_saveexec_b64 s[12:13], s[46:47]
	ds_read_b32 v60, v114 offset:256
	s_or_b64 exec, exec, s[12:13]
	s_and_saveexec_b64 s[12:13], s[48:49]
	ds_read_b32 v59, v114 offset:512
	s_or_b64 exec, exec, s[12:13]
	v_mov_b32_e32 v61, 0
	v_mov_b32_e32 v62, 0
	s_and_saveexec_b64 s[12:13], s[50:51]
	ds_read_b32 v62, v114 offset:768
	s_or_b64 exec, exec, s[12:13]
	s_and_saveexec_b64 s[12:13], s[52:53]
	ds_read_b32 v61, v114 offset:1024
	s_or_b64 exec, exec, s[12:13]
	v_mov_b32_e32 v63, 0
	v_mov_b32_e32 v64, 0
	s_and_saveexec_b64 s[12:13], s[54:55]
	ds_read_b32 v64, v114 offset:1280
	s_or_b64 exec, exec, s[12:13]
	s_and_saveexec_b64 s[12:13], s[56:57]
	ds_read_b32 v63, v114 offset:1536
	s_or_b64 exec, exec, s[12:13]
	s_waitcnt lgkmcnt(0)
	v_add_f32_e32 v58, v58, v60
	v_add_f32_e32 v58, v58, v59
	v_add_f32_e32 v58, v58, v62
	v_add_f32_e32 v58, v58, v61
	v_add_f32_e32 v60, v58, v64
	ds_read2st64_b32 v[58:59], v159 offset1:1
	v_add_f32_e32 v177, v60, v63
	ds_read2st64_b32 v[60:61], v159 offset0:2 offset1:3
	ds_read2st64_b32 v[62:63], v159 offset0:4 offset1:5
	ds_read2st64_b32 v[64:65], v159 offset0:6 offset1:7
	s_waitcnt lgkmcnt(3)
	v_add_f32_e32 v58, v177, v58
	v_add_f32_e32 v59, v177, v59
	ds_write2st64_b32 v159, v58, v59 offset1:1
	s_waitcnt lgkmcnt(3)
	v_add_f32_e32 v58, v177, v60
	v_add_f32_e32 v59, v177, v61
	ds_write2st64_b32 v159, v58, v59 offset0:2 offset1:3
	s_waitcnt lgkmcnt(3)
	v_add_f32_e32 v58, v177, v62
	v_add_f32_e32 v59, v177, v63
	ds_write2st64_b32 v159, v58, v59 offset0:4 offset1:5
	s_waitcnt lgkmcnt(3)
	v_add_f32_e32 v58, v177, v64
	v_add_f32_e32 v59, v177, v65
	ds_write2st64_b32 v159, v58, v59 offset0:6 offset1:7
	s_waitcnt lgkmcnt(0)
	s_barrier
	ds_read_b128 v[58:61], v112
	ds_read_b128 v[62:65], v112 offset:16
	s_waitcnt lgkmcnt(1)
	v_mul_f32_e32 v177, 0x3fb8aa3b, v58
	v_exp_f32_e32 v177, v177
	s_and_saveexec_b64 s[12:13], s[42:43]
	ds_write_b32 v115, v177
	s_or_b64 exec, exec, s[12:13]
	v_mul_f32_e32 v178, 0x3fb8aa3b, v59
	v_exp_f32_e32 v178, v178
	s_and_saveexec_b64 s[12:13], s[42:43]
	ds_write_b32 v115, v178 offset:4
	s_or_b64 exec, exec, s[12:13]
	v_mul_f32_e32 v179, 0x3fb8aa3b, v60
	v_exp_f32_e32 v179, v179
	s_and_saveexec_b64 s[12:13], s[42:43]
	ds_write_b32 v115, v179 offset:8
	s_or_b64 exec, exec, s[12:13]
	v_mul_f32_e32 v180, 0x3fb8aa3b, v61
	v_exp_f32_e32 v180, v180
	s_and_saveexec_b64 s[12:13], s[42:43]
	ds_write_b32 v115, v180 offset:12
	s_or_b64 exec, exec, s[12:13]
	s_waitcnt lgkmcnt(0)
	v_mul_f32_e32 v181, 0x3fb8aa3b, v62
	v_exp_f32_e32 v181, v181
	s_and_saveexec_b64 s[12:13], s[42:43]
	ds_write_b32 v115, v181 offset:16
	s_or_b64 exec, exec, s[12:13]
	v_mul_f32_e32 v182, 0x3fb8aa3b, v63
	v_exp_f32_e32 v182, v182
	s_and_saveexec_b64 s[12:13], s[42:43]
	ds_write_b32 v115, v182 offset:20
	s_or_b64 exec, exec, s[12:13]
	v_mul_f32_e32 v183, 0x3fb8aa3b, v64
	v_exp_f32_e32 v183, v183
	s_and_saveexec_b64 s[12:13], s[42:43]
	ds_write_b32 v115, v183 offset:24
	s_or_b64 exec, exec, s[12:13]
	v_mul_f32_e32 v184, 0x3fb8aa3b, v65
	v_exp_f32_e32 v184, v184
	s_and_saveexec_b64 s[12:13], s[42:43]
	ds_write_b32 v115, v184 offset:28
	s_or_b64 exec, exec, s[12:13]
	v_add_f32_e32 v33, v33, v41
	v_mul_f32_e32 v33, 0xbfb8aa3b, v33
	v_add_f32_e32 v32, v32, v40
	v_exp_f32_e32 v33, v33
	v_mul_f32_e32 v32, 0xbfb8aa3b, v32
	v_exp_f32_e32 v32, v32
	v_add_f32_e32 v31, v31, v39
	v_add_f32_e32 v26, v26, v34
	v_add_f32_e32 v34, v146, v147
	v_mul_f32_e32 v31, 0xbfb8aa3b, v31
	v_add_f32_e32 v33, 1.0, v33
	v_max_f32_e32 v34, 0x179abe15, v34
	v_exp_f32_e32 v31, v31
	v_rcp_f32_e32 v33, v33
	v_sub_f32_e32 v39, v65, v57
	v_rsq_f32_e32 v34, v34
	v_add_f32_e32 v32, 1.0, v32
	v_mul_f32_e32 v39, 0x3fb8aa3b, v39
	v_add_f32_e32 v30, v30, v38
	v_rcp_f32_e32 v32, v32
	v_mul_f32_e32 v38, 0xbfb8aa3b, v65
	v_exp_f32_e32 v39, v39
	v_exp_f32_e32 v38, v38
	v_add_f32_e32 v28, v28, v36
	v_mul_f32_e32 v30, 0xbfb8aa3b, v30
	v_add_f32_e32 v31, 1.0, v31
	v_add_f32_e32 v36, -1.0, v33
	v_mul_f32_e32 v40, 0xbfb8aa3b, v64
	v_add_f32_e32 v29, v29, v37
	v_exp_f32_e32 v30, v30
	v_rcp_f32_e32 v31, v31
	v_fma_f32 v36, v36, v53, 1.0
	v_mul_f32_e32 v37, v176, v34
	v_exp_f32_e32 v40, v40
	v_mul_f32_e32 v36, v36, v175
	v_mul_f32_e32 v39, v37, v39
	v_mul_f32_e64 v33, v37, -v33
	v_add_f32_e32 v37, -1.0, v32
	v_mul_f32_e32 v29, 0xbfb8aa3b, v29
	v_mul_f32_e32 v33, v33, v38
	v_mul_f32_e32 v36, v36, v38
	v_fma_f32 v37, v37, v52, 1.0
	v_mul_f32_e32 v38, v174, v34
	v_sub_f32_e32 v41, v64, v56
	v_mul_f32_e32 v52, 0xbfb8aa3b, v63
	v_exp_f32_e32 v29, v29
	v_mul_f32_e32 v37, v37, v173
	v_mul_f32_e32 v41, 0x3fb8aa3b, v41
; __device__ __forceinline__ unsigned pk2(float lo, float hi) { const f32x2_cv v = {lo, hi}; const bf16x2_cv b = __builtin_convertvector(v, bf16x2_cv); return __builtin_bit_cast(unsigned, b); }
; template <bool PA> ...
;     ...
;                 const f32x4_t c0 = *(const f32x4_t*)(cumb + j * 64 + c8), c1 = *(const f32x4_t*)(cumb + j * 64 + c8 + 4);
;                 float ah[8], bh[8], kh[8], rh[8];
; #pragma unroll
;                 for (int e = 0; e < 8; ++e) { const float cu = e < 4 ? c0[e & 3] : c1[e & 3]; const float Wt = __expf(cu), iW = __expf(-cu), Wm1 = __expf(cu - lw[e]);
;                     ah[e] = kk[e] * Wm1; bh[e] = -(kk[e] * av[e]) * iW; kh[e] = kd[e] * iW; rh[e] = rv[e] * Wt;
;                     if (j == 63) wc[c8 + e] = Wt; }
;                 u32x4_t w;
;                 w.x = pk2(ah[0], ah[1]); w.y = pk2(ah[2], ah[3]); w.z = pk2(ah[4], ah[5]); w.w = pk2(ah[6], ah[7]); *(u32x4_t*)(MAT(0) + j * 72 + c8) = w;
;                 u32x4_t wb, wk;
;                 wb.x = pk2(bh[0], bh[1]); wb.y = pk2(bh[2], bh[3]); wb.z = pk2(bh[4], bh[5]); wb.w = pk2(bh[6], bh[7]); *(u32x4_t*)(MAT(1) + j * 72 + c8) = wb;
;                 wk.x = pk2(kh[0], kh[1]); wk.y = pk2(kh[2], kh[3]); wk.z = pk2(kh[4], kh[5]); wk.w = pk2(kh[6], kh[7]); *(u32x4_t*)(MAT(2) + j * 72 + c8) = wk;
;                 w.x = pk2(rh[0], rh[1]); w.y = pk2(rh[2], rh[3]); w.z = pk2(rh[4], rh[5]); w.w = pk2(rh[6], rh[7]); *(u32x4_t*)(MAT(3) + j * 72 + c8) = w;
;                 { const unsigned wba[4] = {wb.x, wb.y, wb.z, wb.w}, wka[4] = {wk.x, wk.y, wk.z, wk.w}, wva[4] = {vraw.x, vraw.y, vraw.z, vraw.w};
; #pragma unroll
;                   for (int q = 0; q < 4; ++q) { bf16* d4 = MAT(4) + (c8 + 2 * q) * 72 + j; bf16* d5 = MAT(5) + (c8 + 2 * q) * 72 + j; bf16* d6 = MAT(6) + (c8 + 2 * q) * 72 + j;
;                       d4[0] = (bf16)(wba[q] & 0xffffu); d4[72] = (bf16)(wba[q] >> 16); d5[0] = (bf16)(wka[q] & 0xffffu); d5[72] = (bf16)(wka[q] >> 16); d6[0] = (bf16)(wva[q] & 0xffffu); d6[72] = (bf16)(wva[q] >> 16); } }
;                 if (haveT) *(u32x4_t*)(MAT(9) + j * 72 + c8) = tld;
;                 st_rm(MAT(7), Sacc, mt, ntb, r16, kq);
;                 if (PA) st_rm(MAT(12), S2acc, mt, ntb, r16, kq);
;             }
	v_mul_f32_e64 v32, v38, -v32
	v_exp_f32_e32 v52, v52
	v_sub_f32_e32 v53, v63, v55
	v_add_f32_e32 v30, 1.0, v30
	v_exp_f32_e32 v41, v41
	v_mul_f32_e32 v32, v32, v40
	v_mul_f32_e32 v37, v37, v40
	v_add_f32_e32 v40, -1.0, v31
	v_mul_f32_e32 v53, 0x3fb8aa3b, v53
	v_mul_f32_e32 v28, 0xbfb8aa3b, v28
	v_rcp_f32_e32 v30, v30
	v_fma_f32 v40, v40, v51, 1.0
	v_mul_f32_e32 v51, v172, v34
	v_exp_f32_e32 v53, v53
	v_exp_f32_e32 v28, v28
	v_mul_f32_e32 v40, v40, v171
	v_mul_f32_e64 v31, v51, -v31
	v_sub_f32_e32 v54, v62, v54
	v_add_f32_e32 v27, v27, v35
	v_add_f32_e32 v29, 1.0, v29
	v_and_b32_e32 v35, 0xffff0000, v25
	v_lshlrev_b32_e32 v25, 16, v25
	v_mul_f32_e32 v31, v31, v52
	v_mul_f32_e32 v40, v40, v52
	v_mul_f32_e32 v52, 0xbfb8aa3b, v62
	v_mul_f32_e32 v54, 0x3fb8aa3b, v54
	v_rcp_f32_e32 v29, v29
	v_mul_f32_e32 v41, v38, v41
	v_mul_f32_e32 v38, v183, v25
	v_and_b32_e32 v25, 0xffff0000, v24
	v_exp_f32_e32 v52, v52
	v_exp_f32_e32 v54, v54
	v_mul_f32_e32 v53, v51, v53
	v_mul_f32_e32 v51, v182, v25
	v_add_f32_e32 v25, -1.0, v30
	v_sub_f32_e32 v49, v61, v49
	v_add_f32_e32 v28, 1.0, v28
	v_fma_f32 v25, v25, v50, 1.0
	v_mul_f32_e32 v55, 0xbfb8aa3b, v61
	v_mul_f32_e32 v49, 0x3fb8aa3b, v49
	v_mul_f32_e32 v27, 0xbfb8aa3b, v27
	v_rcp_f32_e32 v28, v28
	v_mul_f32_e32 v25, v25, v169
	v_mul_f32_e32 v50, v170, v34
	v_exp_f32_e32 v55, v55
	v_exp_f32_e32 v49, v49
	v_exp_f32_e32 v27, v27
	v_mul_f32_e32 v54, v50, v54
	v_mul_f32_e64 v30, v50, -v30
	v_mul_f32_e32 v50, v25, v52
	v_add_f32_e32 v25, -1.0, v29
	v_lshlrev_b32_e32 v24, 16, v24
	v_fma_f32 v25, v25, v45, 1.0
	v_mul_f32_e32 v45, v168, v34
	v_mul_f32_e32 v30, v30, v52
	v_mul_f32_e32 v52, v181, v24
	v_and_b32_e32 v24, 0xffff0000, v23
	v_mul_f32_e32 v25, v25, v167
	v_mul_f32_e64 v29, v45, -v29
	v_sub_f32_e32 v48, v60, v48
	v_mul_f32_e32 v49, v45, v49
	v_mul_f32_e32 v29, v29, v55
	v_mul_f32_e32 v45, v25, v55
	v_mul_f32_e32 v55, v180, v24
	v_add_f32_e32 v24, -1.0, v28
	v_mul_f32_e32 v48, 0x3fb8aa3b, v48
	v_add_f32_e32 v27, 1.0, v27
	v_fma_f32 v24, v24, v44, 1.0
	v_mul_f32_e32 v44, 0xbfb8aa3b, v60
	v_exp_f32_e32 v48, v48
	v_rcp_f32_e32 v27, v27
	v_exp_f32_e32 v44, v44
	v_mul_f32_e32 v25, v166, v34
	v_mul_f32_e32 v24, v24, v165
	v_mul_f32_e32 v48, v25, v48
	v_mul_f32_e64 v25, v25, -v28
	v_sub_f32_e32 v47, v59, v47
	v_mul_f32_e32 v26, 0xbfb8aa3b, v26
	v_mul_f32_e32 v28, v25, v44
	v_mul_f32_e32 v44, v24, v44
	v_add_f32_e32 v24, -1.0, v27
	v_mul_f32_e32 v47, 0x3fb8aa3b, v47
	v_exp_f32_e32 v26, v26
	v_fma_f32 v24, v24, v43, 1.0
	v_mul_f32_e32 v43, 0xbfb8aa3b, v59
	v_exp_f32_e32 v47, v47
	v_exp_f32_e32 v43, v43
	v_mul_f32_e32 v25, v164, v34
	v_add_f32_e32 v26, 1.0, v26
	v_mul_f32_e32 v24, v24, v163
	v_mul_f32_e32 v47, v25, v47
	v_mul_f32_e64 v25, v25, -v27
	v_rcp_f32_e32 v26, v26
	v_mul_f32_e32 v27, v25, v43
	v_mul_f32_e32 v43, v24, v43
	v_mul_f32_e32 v24, v162, v34
	v_sub_f32_e32 v34, v58, v46
	v_mul_f32_e32 v34, 0x3fb8aa3b, v34
	v_lshlrev_b32_e32 v23, 16, v23
	v_mul_f32_e32 v25, 0xbfb8aa3b, v58
	v_exp_f32_e32 v34, v34
	v_mul_f32_e32 v56, v179, v23
	v_and_b32_e32 v23, 0xffff0000, v22
	v_exp_f32_e32 v25, v25
	v_mul_f32_e32 v57, v178, v23
	v_add_f32_e32 v23, -1.0, v26
	v_fma_f32 v23, v23, v42, 1.0
	v_lshlrev_b32_e32 v22, 16, v22
	v_mul_f32_e32 v23, v23, v161
	v_mul_f32_e32 v34, v24, v34
	v_mul_f32_e64 v24, v24, -v26
	v_mul_f32_e32 v35, v184, v35
	v_mul_f32_e32 v26, v24, v25
	v_mul_f32_e32 v42, v23, v25
	v_mul_f32_e32 v46, v177, v22
	v_cvt_pk_bf16_f32 v22, v34, v47
	v_cvt_pk_bf16_f32 v23, v48, v49
	v_cvt_pk_bf16_f32 v24, v54, v53
	v_cvt_pk_bf16_f32 v25, v41, v39
	ds_write_b128 v68, v[22:25]
	v_cvt_pk_bf16_f32 v22, v26, v27
	v_cvt_pk_bf16_f32 v23, v28, v29
	v_cvt_pk_bf16_f32 v24, v30, v31
	v_cvt_pk_bf16_f32 v25, v32, v33
	v_cvt_pk_bf16_f32 v26, v42, v43
	v_cvt_pk_bf16_f32 v27, v44, v45
	v_cvt_pk_bf16_f32 v28, v50, v40
	v_cvt_pk_bf16_f32 v29, v37, v36
	v_cvt_pk_bf16_f32 v30, v46, v57
	v_cvt_pk_bf16_f32 v31, v56, v55
	v_cvt_pk_bf16_f32 v32, v52, v51
	v_cvt_pk_bf16_f32 v33, v38, v35
	ds_write_b128 v68, v[22:25] offset:9216
	ds_write_b128 v68, v[26:29] offset:18432
	ds_write_b128 v68, v[30:33] offset:27648
	ds_write_b16 v154, v22 offset:36864
	ds_write_b16_d16_hi v154, v22 offset:37008
	ds_write_b16 v154, v26 offset:46080
	ds_write_b16_d16_hi v154, v26 offset:46224
	s_nop 0
	ds_write_b16 v154, v18 offset:55296
	ds_write_b16_d16_hi v154, v18 offset:55440
	ds_write_b16 v154, v23 offset:37152
	ds_write_b16_d16_hi v154, v23 offset:37296
	ds_write_b16 v154, v27 offset:46368
	ds_write_b16_d16_hi v154, v27 offset:46512
	ds_write_b16 v154, v19 offset:55584
	ds_write_b16_d16_hi v154, v19 offset:55728
	ds_write_b16 v185, v24 offset:37440
	ds_write_b16_d16_hi v185, v24 offset:37584
	ds_write_b16 v185, v28 offset:46656
	ds_write_b16_d16_hi v185, v28 offset:46800
	ds_write_b16 v185, v20 offset:55872
	ds_write_b16_d16_hi v185, v20 offset:56016
	ds_write_b16 v185, v25 offset:37728
	ds_write_b16_d16_hi v185, v25 offset:37872
	ds_write_b16 v185, v29 offset:46944
	ds_write_b16_d16_hi v185, v29 offset:47088
	ds_write_b16 v185, v21 offset:56160
	ds_write_b16_d16_hi v185, v21 offset:56304
	v_cvt_pk_bf16_f32 v18, v2, v3
	v_cvt_pk_bf16_f32 v19, v4, v5
	ds_write_b16 v116, v18 offset:64512
	ds_write_b16_d16_hi v116, v18 offset:64656
	ds_write_b16 v116, v19 offset:64800
	ds_write_b16_d16_hi v116, v19 offset:64944
	v_cvt_pk_bf16_f32 v18, v6, v7
	v_cvt_pk_bf16_f32 v0, v8, v0
	ds_write_b16 v116, v18 offset:64544
	ds_write_b16_d16_hi v116, v18 offset:64688
	ds_write_b16 v116, v0 offset:64832
	ds_write_b16_d16_hi v116, v0 offset:64976
	v_cvt_pk_bf16_f32 v0, v10, v11
	v_cvt_pk_bf16_f32 v18, v12, v13
	ds_write_b16 v117, v0
	ds_write_b16_d16_hi v117, v0 offset:144
	ds_write_b16 v117, v18 offset:288
	ds_write_b16_d16_hi v117, v18 offset:432
	v_cvt_pk_bf16_f32 v0, v14, v15
	v_cvt_pk_bf16_f32 v18, v16, v17
	ds_write_b16 v117, v0 offset:32
	ds_write_b16_d16_hi v117, v0 offset:176
	ds_write_b16 v117, v18 offset:320
	ds_write_b16_d16_hi v117, v18 offset:464
	s_waitcnt lgkmcnt(0)
	s_barrier
; template <bool PA> ...
;     ...
;             f32x4_t Pacc[2], Tacc[2], Xacc[2], Yacc[2], tmp[2];
;             const f32x4_t z4 = (f32x4_t){0.f, 0.f, 0.f, 0.f};
;             Tacc[0] = z4; Tacc[1] = z4;
;             if (!haveT) {
;             Pacc[0] = z4; Pacc[1] = z4; mm2(Pacc, MAT(0), MAT(1), mt, ntb, r16, kq);
; #pragma unroll
;             for (int i = 0; i < 2; ++i)
; #pragma unroll
;                 for (int e = 0; e < 4; ++e) { const int t = 16 * mt + 4 * kq + e, s = 16 * (ntb + i) + r16; Pacc[i][e] = (s < t) ? Pacc[i][e] : 0.f; Tacc[i][e] = Pacc[i][e] + ((s == t) ? 1.f : 0.f); }
;             st_rm(MAT(8), Pacc, mt, ntb, r16, kq); st_tr(MAT(9), Pacc, mt, ntb, r16, kq);
;             }
;             tmp[0] = z4; tmp[1] = z4; mm2(tmp, MAT(0), MAT(2), mt, ntb, r16, kq);
; #pragma unroll
;             for (int i = 0; i < 2; ++i)
; #pragma unroll
;                 for (int e = 0; e < 4; ++e) { const int t = 16 * mt + 4 * kq + e, s = 16 * (ntb + i) + r16; tmp[i][e] = (s < t) ? tmp[i][e] : 0.f; }
;             st_rm(MAT(10), tmp, mt, ntb, r16, kq);
;             f32x4_t X2acc[2]; X2acc[0] = z4; X2acc[1] = z4;
;             if (PA) mm2(X2acc, MAT(0), MAT(12), mt, ntb, r16, kq);
;             if (!PA) {
;             tmp[0] = z4; tmp[1] = z4; mm2(tmp, MAT(3), MAT(1), mt, ntb, r16, kq);
; #pragma unroll
;             for (int i = 0; i < 2; ++i)
; #pragma unroll
;                 for (int e = 0; e < 4; ++e) { const int t = 16 * mt + 4 * kq + e, s = 16 * (ntb + i) + r16; tmp[i][e] = (s <= t) ? tmp[i][e] : 0.f; }
;             st_rm(MAT(11), tmp, mt, ntb, r16, kq);
;             tmp[0] = z4; tmp[1] = z4; mm2(tmp, MAT(3), MAT(2), mt, ntb, r16, kq);
; #pragma unroll
;             for (int i = 0; i < 2; ++i)
; #pragma unroll
;                 for (int e = 0; e < 4; ++e) { const int t = 16 * mt + 4 * kq + e, s = 16 * (ntb + i) + r16; tmp[i][e] = (s <= t) ? tmp[i][e] : 0.f; }
;             st_rm(MAT(12), tmp, mt, ntb, r16, kq);
;             }
;             Xacc[0] = z4; Xacc[1] = z4; mm2(Xacc, MAT(0), MAT(7), mt, ntb, r16, kq);
;             Yacc[0] = z4; Yacc[1] = z4; if (!PA) mm2(Yacc, MAT(3), MAT(7), mt, ntb, r16, kq);
;             __syncthreads();
;             if (!haveT) {
;             tmp[0] = z4; tmp[1] = z4; mm2(tmp, MAT(8), MAT(9), mt, ntb, r16, kq);
	ds_read_b128 v[186:189], v69
	ds_read_b128 v[190:193], v118 offset:9216
	ds_read_b128 v[204:207], v118 offset:11520
	ds_read_b128 v[208:211], v69 offset:64
	ds_read_b128 v[212:215], v118 offset:9280
	ds_read_b128 v[216:219], v118 offset:11584
	ds_read_b128 v[220:223], v69
	ds_read_b128 v[224:227], v118 offset:18432
	s_nop 0
	s_nop 0
	s_nop 0
	s_waitcnt lgkmcnt(6)
	v_mfma_f32_16x16x32_bf16 v[22:25], v[186:189], v[190:193], 0
	ds_read_b128 v[190:193], v118 offset:20736
	s_waitcnt lgkmcnt(6)
	v_mfma_f32_16x16x32_bf16 v[18:21], v[186:189], v[204:207], 0
	ds_read_b128 v[186:189], v69 offset:64
	ds_read_b128 v[204:207], v118 offset:18496
	s_nop 0
	s_nop 0
	s_waitcnt lgkmcnt(6)
	v_mfma_f32_16x16x32_bf16 v[22:25], v[208:211], v[212:215], v[22:25]
	ds_read_b128 v[212:215], v118 offset:20800
	s_nop 0
	s_waitcnt lgkmcnt(6)
	v_mfma_f32_16x16x32_bf16 v[18:21], v[208:211], v[216:219], v[18:21]
	s_nop 4
	v_cndmask_b32_e64 v0, 0, v22, s[58:59]
	v_cndmask_b32_e64 v22, v23, 0, s[60:61]
	v_cndmask_b32_e64 v23, 0, v24, s[62:63]
	v_cndmask_b32_e64 v24, 0, v25, s[64:65]
	v_cndmask_b32_e64 v25, 0, v18, s[66:67]
	v_cndmask_b32_e64 v26, v19, 0, s[68:69]
	v_cndmask_b32_e64 v27, 0, v20, s[70:71]
	v_cndmask_b32_e64 v21, 0, v21, s[72:73]
	v_add_f32_e32 v65, v143, v21
	v_cvt_pk_bf16_f32 v18, v0, v22
	v_cvt_pk_bf16_f32 v20, v25, v26
	v_cvt_pk_bf16_f32 v21, v27, v21
	v_cvt_pk_bf16_f32 v19, v23, v24
	ds_write_b16 v119, v18
	ds_write_b16_d16_hi v119, v18 offset:144
	ds_write_b16 v119, v19 offset:288
	ds_write_b16_d16_hi v119, v19 offset:432
	ds_write_b16 v119, v20 offset:32
	ds_write_b16_d16_hi v119, v20 offset:176
	ds_write_b16 v119, v21 offset:320
	ds_write_b16_d16_hi v119, v21 offset:464
	ds_write_b64 v120, v[18:19]
	ds_write_b64 v120, v[20:21] offset:2304
	v_add_f32_e32 v59, v137, v22
	v_add_f32_e32 v60, v138, v23
	v_add_f32_e32 v61, v139, v24
	v_add_f32_e32 v62, v140, v25
	v_add_f32_e32 v63, v141, v26
	v_add_f32_e32 v64, v142, v27
	s_nop 0
	s_nop 0
	s_nop 0
	s_waitcnt lgkmcnt(0)
	v_mfma_f32_16x16x32_bf16 v[22:25], v[220:223], v[224:227], 0
	v_add_f32_e32 v58, v136, v0
	s_waitcnt lgkmcnt(0)
	v_mfma_f32_16x16x32_bf16 v[18:21], v[220:223], v[190:193], 0
	s_nop 0
	s_nop 0
	s_waitcnt lgkmcnt(0)
	v_mfma_f32_16x16x32_bf16 v[22:25], v[186:189], v[204:207], v[22:25]
	s_nop 0
	s_waitcnt lgkmcnt(0)
	v_mfma_f32_16x16x32_bf16 v[18:21], v[186:189], v[212:215], v[18:21]
	s_nop 4
	v_cndmask_b32_e64 v0, 0, v22, s[58:59]
	v_cndmask_b32_e64 v22, v23, 0, s[60:61]
	v_cndmask_b32_e64 v23, 0, v24, s[62:63]
	v_cndmask_b32_e64 v24, 0, v25, s[64:65]
	v_cndmask_b32_e64 v18, 0, v18, s[66:67]
	v_cndmask_b32_e64 v19, v19, 0, s[68:69]
	v_cvt_pk_bf16_f32 v0, v0, v22
	v_cndmask_b32_e64 v20, 0, v20, s[70:71]
	v_cndmask_b32_e64 v21, 0, v21, s[72:73]
	v_cvt_pk_bf16_f32 v22, v23, v24
	ds_write_b16 v121, v0
	ds_write_b16_d16_hi v121, v0 offset:144
	ds_write_b16 v121, v22 offset:288
	ds_write_b16_d16_hi v121, v22 offset:432
	v_cvt_pk_bf16_f32 v0, v18, v19
	v_cvt_pk_bf16_f32 v18, v20, v21
	ds_write_b16 v121, v0 offset:32
	ds_write_b16_d16_hi v121, v0 offset:176
	ds_write_b16 v121, v18 offset:320
	ds_write_b16_d16_hi v121, v18 offset:464
	ds_read_b128 v[22:25], v69
	ds_read_b128 v[42:45], v122
	ds_read_b128 v[46:49], v122 offset:2304
	ds_read_b128 v[18:21], v69 offset:64
	ds_read_b128 v[54:57], v122 offset:64
	ds_read_b128 v[50:53], v122 offset:2368
	ds_read_b128 v[38:41], v118 offset:64512
	ds_read_b128 v[34:37], v123
	ds_read_b128 v[30:33], v118 offset:64576
	ds_read_b128 v[26:29], v124
	s_waitcnt lgkmcnt(0)
	s_barrier
	ds_read_b128 v[186:189], v125
	ds_read_b128 v[190:193], v126
	ds_read_b128 v[204:207], v126 offset:2304
	ds_read_b128 v[208:211], v125 offset:64
	ds_read_b128 v[212:215], v126 offset:64
	ds_read_b128 v[216:219], v126 offset:2368
	s_nop 0
	s_nop 0
	s_nop 0
	s_waitcnt lgkmcnt(4)
	v_mfma_f32_16x16x32_bf16 v[166:169], v[186:189], v[190:193], 0
	v_cvt_pk_bf16_f32 v0, v58, v59
	s_waitcnt lgkmcnt(3)
	v_mfma_f32_16x16x32_bf16 v[162:165], v[186:189], v[204:207], 0
	s_nop 0
	s_nop 0
	s_waitcnt lgkmcnt(1)
	v_mfma_f32_16x16x32_bf16 v[166:169], v[208:211], v[212:215], v[166:169]
	s_nop 0
	s_waitcnt lgkmcnt(0)
	v_mfma_f32_16x16x32_bf16 v[162:165], v[208:211], v[216:219], v[162:165]
	s_nop 4
	v_cvt_pk_bf16_f32 v146, v166, v167
	v_cvt_pk_bf16_f32 v147, v168, v169
	ds_write_b16 v116, v146
	ds_write_b16_d16_hi v116, v146 offset:144
	ds_write_b16 v116, v147 offset:288
	ds_write_b16_d16_hi v116, v147 offset:432
	v_cvt_pk_bf16_f32 v162, v162, v163
	v_cvt_pk_bf16_f32 v163, v164, v165
	ds_write_b16 v116, v162 offset:32
	ds_write_b16_d16_hi v116, v162 offset:176
	ds_write_b16 v116, v163 offset:320
	ds_write_b16_d16_hi v116, v163 offset:464
	ds_write_b64 v127, v[146:147] offset:9216
	ds_write_b64 v127, v[162:163] offset:11520
	v_cvt_pk_bf16_f32 v146, v60, v61
	ds_write_b16 v116, v0 offset:18432
	ds_write_b16_d16_hi v116, v0 offset:18576
	ds_write_b16 v116, v146 offset:18720
	ds_write_b16_d16_hi v116, v146 offset:18864
	v_cvt_pk_bf16_f32 v0, v62, v63
	v_cvt_pk_bf16_f32 v146, v64, v65
	ds_write_b16 v116, v0 offset:18464
	ds_write_b16_d16_hi v116, v0 offset:18608
	ds_write_b16 v116, v146 offset:18752
	ds_write_b16_d16_hi v116, v146 offset:18896
	s_waitcnt lgkmcnt(0)
	s_barrier
; template <bool PA> ...
;     ...
; #pragma unroll
;             for (int i = 1; i <= 5; ++i) {
;                 bf16* Pc = (i & 1) ? MAT(0) : MAT(8); bf16* PcT = (i & 1) ? MAT(1) : MAT(9); bf16* Pn = (i & 1) ? MAT(8) : MAT(0); bf16* PnT = (i & 1) ? MAT(9) : MAT(1);
;                 bf16* Tc = (i & 1) ? MAT(2) : MAT(3); bf16* Tn = (i & 1) ? MAT(3) : MAT(2);
;                 mm2(Tacc, Tc, PcT, mt, ntb, r16, kq);
;                 if (i < 5) { tmp[0] = z4; tmp[1] = z4; mm2(tmp, Pc, PcT, mt, ntb, r16, kq); st_rm(Pn, tmp, mt, ntb, r16, kq); st_tr(PnT, tmp, mt, ntb, r16, kq); }
;                 st_rm(Tn, Tacc, mt, ntb, r16, kq);
;                 __syncthreads();
;             }
	ds_read_b128 v[186:189], v69 offset:18432
	ds_read_b128 v[190:193], v118 offset:9216
	ds_read_b128 v[204:207], v118 offset:11520
	ds_read_b128 v[208:211], v69 offset:18496
	ds_read_b128 v[212:215], v118 offset:9280
	ds_read_b128 v[216:219], v118 offset:11584
	ds_read_b128 v[220:223], v69
	ds_read_b128 v[224:227], v69 offset:64
	s_nop 0
	s_nop 0
	s_nop 0
	s_waitcnt lgkmcnt(6)
	v_mfma_f32_16x16x32_bf16 v[58:61], v[186:189], v[190:193], v[58:61]
	s_waitcnt lgkmcnt(5)
	v_mfma_f32_16x16x32_bf16 v[62:65], v[186:189], v[204:207], v[62:65]
	s_nop 0
	s_nop 0
	s_nop 0
	s_waitcnt lgkmcnt(3)
	v_mfma_f32_16x16x32_bf16 v[58:61], v[208:211], v[212:215], v[58:61]
	s_waitcnt lgkmcnt(2)
	v_mfma_f32_16x16x32_bf16 v[62:65], v[208:211], v[216:219], v[62:65]
	s_nop 0
	s_nop 4
	v_cvt_pk_bf16_f32 v0, v58, v59
	s_waitcnt lgkmcnt(1)
	v_mfma_f32_16x16x32_bf16 v[166:169], v[220:223], v[190:193], 0
	v_mfma_f32_16x16x32_bf16 v[162:165], v[220:223], v[204:207], 0
	s_nop 0
	s_waitcnt lgkmcnt(0)
	v_mfma_f32_16x16x32_bf16 v[166:169], v[224:227], v[212:215], v[166:169]
	s_nop 7
	v_cvt_pk_bf16_f32 v146, v166, v167
	v_mfma_f32_16x16x32_bf16 v[162:165], v[224:227], v[216:219], v[162:165]
	v_cvt_pk_bf16_f32 v147, v168, v169
	ds_write_b16 v155, v146
	ds_write_b16_d16_hi v155, v146 offset:144
	ds_write_b16 v155, v147 offset:288
	ds_write_b16_d16_hi v155, v147 offset:432
	s_nop 2
	v_cvt_pk_bf16_f32 v162, v162, v163
	v_cvt_pk_bf16_f32 v163, v164, v165
	ds_write_b16 v155, v162 offset:32
	ds_write_b16_d16_hi v155, v162 offset:176
	ds_write_b16 v155, v163 offset:320
	ds_write_b16_d16_hi v155, v163 offset:464
	ds_write_b64 v120, v[146:147]
	ds_write_b64 v120, v[162:163] offset:2304
	v_cvt_pk_bf16_f32 v146, v60, v61
	ds_write_b16 v156, v0 offset:27648
	ds_write_b16_d16_hi v156, v0 offset:27792
	ds_write_b16 v156, v146 offset:27936
	ds_write_b16_d16_hi v156, v146 offset:28080
	v_cvt_pk_bf16_f32 v0, v62, v63
	v_cvt_pk_bf16_f32 v146, v64, v65
	ds_write_b16 v156, v0 offset:27680
	ds_write_b16_d16_hi v156, v0 offset:27824
	ds_write_b16 v156, v146 offset:27968
	ds_write_b16_d16_hi v156, v146 offset:28112
	s_waitcnt lgkmcnt(0)
	s_barrier
	ds_read_b128 v[186:189], v69 offset:27648
	ds_read_b128 v[190:193], v126
	ds_read_b128 v[204:207], v126 offset:2304
	ds_read_b128 v[208:211], v69 offset:27712
	ds_read_b128 v[212:215], v126 offset:64
	ds_read_b128 v[216:219], v126 offset:2368
	ds_read_b128 v[220:223], v125
	ds_read_b128 v[224:227], v125 offset:64
	s_nop 0
	s_nop 0
	s_nop 0
	s_waitcnt lgkmcnt(6)
	v_mfma_f32_16x16x32_bf16 v[58:61], v[186:189], v[190:193], v[58:61]
	s_waitcnt lgkmcnt(5)
	v_mfma_f32_16x16x32_bf16 v[62:65], v[186:189], v[204:207], v[62:65]
	s_nop 0
	s_nop 0
	s_nop 0
	s_waitcnt lgkmcnt(3)
	v_mfma_f32_16x16x32_bf16 v[58:61], v[208:211], v[212:215], v[58:61]
	s_waitcnt lgkmcnt(2)
	v_mfma_f32_16x16x32_bf16 v[62:65], v[208:211], v[216:219], v[62:65]
	s_nop 0
	s_nop 4
	v_cvt_pk_bf16_f32 v0, v58, v59
	s_waitcnt lgkmcnt(1)
	v_mfma_f32_16x16x32_bf16 v[166:169], v[220:223], v[190:193], 0
	v_mfma_f32_16x16x32_bf16 v[162:165], v[220:223], v[204:207], 0
	s_nop 0
	s_waitcnt lgkmcnt(0)
	v_mfma_f32_16x16x32_bf16 v[166:169], v[224:227], v[212:215], v[166:169]
	s_nop 7
	v_cvt_pk_bf16_f32 v146, v166, v167
	v_mfma_f32_16x16x32_bf16 v[162:165], v[224:227], v[216:219], v[162:165]
	v_cvt_pk_bf16_f32 v147, v168, v169
	ds_write_b16 v156, v146
	ds_write_b16_d16_hi v156, v146 offset:144
	ds_write_b16 v156, v147 offset:288
	ds_write_b16_d16_hi v156, v147 offset:432
	s_nop 2
	v_cvt_pk_bf16_f32 v162, v162, v163
	v_cvt_pk_bf16_f32 v163, v164, v165
	ds_write_b16 v156, v162 offset:32
	ds_write_b16_d16_hi v156, v162 offset:176
	ds_write_b16 v156, v163 offset:320
	ds_write_b16_d16_hi v156, v163 offset:464
	ds_write_b64 v127, v[146:147] offset:9216
	ds_write_b64 v127, v[162:163] offset:11520
	v_cvt_pk_bf16_f32 v146, v60, v61
	ds_write_b16 v156, v0 offset:18432
	ds_write_b16_d16_hi v156, v0 offset:18576
	ds_write_b16 v156, v146 offset:18720
	ds_write_b16_d16_hi v156, v146 offset:18864
	v_cvt_pk_bf16_f32 v0, v62, v63
	v_cvt_pk_bf16_f32 v146, v64, v65
	ds_write_b16 v156, v0 offset:18464
	ds_write_b16_d16_hi v156, v0 offset:18608
	ds_write_b16 v156, v146 offset:18752
	ds_write_b16_d16_hi v156, v146 offset:18896
	s_waitcnt lgkmcnt(0)
	s_barrier
	ds_read_b128 v[186:189], v69 offset:18432
	ds_read_b128 v[190:193], v118 offset:9216
	ds_read_b128 v[204:207], v118 offset:11520
	ds_read_b128 v[208:211], v69 offset:18496
	ds_read_b128 v[212:215], v118 offset:9280
	ds_read_b128 v[216:219], v118 offset:11584
	ds_read_b128 v[220:223], v69
	ds_read_b128 v[224:227], v69 offset:64
	s_nop 0
	s_nop 0
	s_nop 0
	s_waitcnt lgkmcnt(6)
	v_mfma_f32_16x16x32_bf16 v[58:61], v[186:189], v[190:193], v[58:61]
	s_waitcnt lgkmcnt(5)
	v_mfma_f32_16x16x32_bf16 v[62:65], v[186:189], v[204:207], v[62:65]
	s_nop 0
	s_nop 0
	s_nop 0
	s_waitcnt lgkmcnt(3)
	v_mfma_f32_16x16x32_bf16 v[58:61], v[208:211], v[212:215], v[58:61]
	s_waitcnt lgkmcnt(2)
	v_mfma_f32_16x16x32_bf16 v[62:65], v[208:211], v[216:219], v[62:65]
	s_nop 0
	s_nop 4
	v_cvt_pk_bf16_f32 v0, v58, v59
	s_waitcnt lgkmcnt(1)
	v_mfma_f32_16x16x32_bf16 v[166:169], v[220:223], v[190:193], 0
	v_mfma_f32_16x16x32_bf16 v[162:165], v[220:223], v[204:207], 0
	s_nop 0
	s_waitcnt lgkmcnt(0)
	v_mfma_f32_16x16x32_bf16 v[166:169], v[224:227], v[212:215], v[166:169]
	s_nop 7
	v_cvt_pk_bf16_f32 v146, v166, v167
	v_mfma_f32_16x16x32_bf16 v[162:165], v[224:227], v[216:219], v[162:165]
	v_cvt_pk_bf16_f32 v147, v168, v169
	ds_write_b16 v155, v146
	ds_write_b16_d16_hi v155, v146 offset:144
	ds_write_b16 v155, v147 offset:288
	ds_write_b16_d16_hi v155, v147 offset:432
	s_nop 2
	v_cvt_pk_bf16_f32 v162, v162, v163
	v_cvt_pk_bf16_f32 v163, v164, v165
	ds_write_b16 v155, v162 offset:32
	ds_write_b16_d16_hi v155, v162 offset:176
	ds_write_b16 v155, v163 offset:320
	ds_write_b16_d16_hi v155, v163 offset:464
	ds_write_b64 v120, v[146:147]
	ds_write_b64 v120, v[162:163] offset:2304
	v_cvt_pk_bf16_f32 v146, v60, v61
	ds_write_b16 v156, v0 offset:27648
	ds_write_b16_d16_hi v156, v0 offset:27792
	ds_write_b16 v156, v146 offset:27936
	ds_write_b16_d16_hi v156, v146 offset:28080
	v_cvt_pk_bf16_f32 v0, v62, v63
	v_cvt_pk_bf16_f32 v146, v64, v65
	ds_write_b16 v156, v0 offset:27680
	ds_write_b16_d16_hi v156, v0 offset:27824
	ds_write_b16 v156, v146 offset:27968
	ds_write_b16_d16_hi v156, v146 offset:28112
	s_waitcnt lgkmcnt(0)
	s_barrier
; template <bool PA> ...
;     ...
;             if (PA) mm2(X2acc, MAT(0), MAT(12), mt, ntb, r16, kq);
;             if (!PA) {
;             tmp[0] = z4; tmp[1] = z4; mm2(tmp, MAT(3), MAT(1), mt, ntb, r16, kq);
; #pragma unroll
;             for (int i = 0; i < 2; ++i)
; #pragma unroll
;                 for (int e = 0; e < 4; ++e) { const int t = 16 * mt + 4 * kq + e, s = 16 * (ntb + i) + r16; tmp[i][e] = (s <= t) ? tmp[i][e] : 0.f; }
;             st_rm(MAT(11), tmp, mt, ntb, r16, kq);
;             tmp[0] = z4; tmp[1] = z4; mm2(tmp, MAT(3), MAT(2), mt, ntb, r16, kq);
; #pragma unroll
;             for (int i = 0; i < 2; ++i)
; #pragma unroll
;                 for (int e = 0; e < 4; ++e) { const int t = 16 * mt + 4 * kq + e, s = 16 * (ntb + i) + r16; tmp[i][e] = (s <= t) ? tmp[i][e] : 0.f; }
;             st_rm(MAT(12), tmp, mt, ntb, r16, kq);
;             }
;             Xacc[0] = z4; Xacc[1] = z4; mm2(Xacc, MAT(0), MAT(7), mt, ntb, r16, kq);
;     ...
; #pragma unroll
;             for (int i = 1; i <= 5; ++i) {
;                 bf16* Pc = (i & 1) ? MAT(0) : MAT(8); bf16* PcT = (i & 1) ? MAT(1) : MAT(9); bf16* Pn = (i & 1) ? MAT(8) : MAT(0); bf16* PnT = (i & 1) ? MAT(9) : MAT(1);
;                 bf16* Tc = (i & 1) ? MAT(2) : MAT(3); bf16* Tn = (i & 1) ? MAT(3) : MAT(2);
;                 mm2(Tacc, Tc, PcT, mt, ntb, r16, kq);
;                 if (i < 5) { tmp[0] = z4; tmp[1] = z4; mm2(tmp, Pc, PcT, mt, ntb, r16, kq); st_rm(Pn, tmp, mt, ntb, r16, kq); st_tr(PnT, tmp, mt, ntb, r16, kq); }
;                 st_rm(Tn, Tacc, mt, ntb, r16, kq);
;                 __syncthreads();
;             }
;             }
;             if (PA && tlow) *(u32x4_t*)(tbuf + ((size_t)strm * NCHA + p) * 2304 + tunit * 8) = *(const u32x4_t*)(MAT(3) + j * 72 + c8);
	ds_read_b128 v[186:189], v69 offset:27648
	ds_read_b128 v[190:193], v126
	ds_read_b128 v[204:207], v126 offset:2304
	ds_read_b128 v[208:211], v69 offset:27712
	ds_read_b128 v[212:215], v126 offset:64
	ds_read_b128 v[216:219], v126 offset:2368
	ds_read_b128 v[220:223], v125
	ds_read_b128 v[224:227], v125 offset:64
	s_nop 0
	s_nop 0
	s_nop 0
	s_waitcnt lgkmcnt(6)
	v_mfma_f32_16x16x32_bf16 v[58:61], v[186:189], v[190:193], v[58:61]
	s_waitcnt lgkmcnt(5)
	v_mfma_f32_16x16x32_bf16 v[62:65], v[186:189], v[204:207], v[62:65]
	s_nop 0
	s_nop 0
	s_nop 0
	s_waitcnt lgkmcnt(3)
	v_mfma_f32_16x16x32_bf16 v[58:61], v[208:211], v[212:215], v[58:61]
	s_waitcnt lgkmcnt(2)
	v_mfma_f32_16x16x32_bf16 v[62:65], v[208:211], v[216:219], v[62:65]
	s_nop 0
	s_nop 4
	v_cvt_pk_bf16_f32 v0, v58, v59
	s_waitcnt lgkmcnt(1)
	v_mfma_f32_16x16x32_bf16 v[166:169], v[220:223], v[190:193], 0
	v_mfma_f32_16x16x32_bf16 v[162:165], v[220:223], v[204:207], 0
	s_nop 0
	s_waitcnt lgkmcnt(0)
	v_mfma_f32_16x16x32_bf16 v[166:169], v[224:227], v[212:215], v[166:169]
	v_mov_b32_e32 v174, v212
	v_mov_b32_e32 v175, v213
	v_mov_b32_e32 v176, v214
	v_mov_b32_e32 v177, v215
	s_nop 7
	v_cvt_pk_bf16_f32 v146, v166, v167
	v_mfma_f32_16x16x32_bf16 v[162:165], v[224:227], v[216:219], v[162:165]
	v_mov_b32_e32 v178, v216
	v_mov_b32_e32 v179, v217
	v_mov_b32_e32 v180, v218
	v_mov_b32_e32 v181, v219
	v_mov_b32_e32 v170, v224
	v_mov_b32_e32 v171, v225
	v_mov_b32_e32 v172, v226
	v_mov_b32_e32 v173, v227
	v_cvt_pk_bf16_f32 v147, v168, v169
	ds_write_b16 v156, v146
	ds_write_b16_d16_hi v156, v146 offset:144
	ds_write_b16 v156, v147 offset:288
	ds_write_b16_d16_hi v156, v147 offset:432
	s_nop 2
	v_cvt_pk_bf16_f32 v162, v162, v163
	v_cvt_pk_bf16_f32 v163, v164, v165
	ds_write_b16 v156, v162 offset:32
	ds_write_b16_d16_hi v156, v162 offset:176
	ds_write_b16 v156, v163 offset:320
	ds_write_b16_d16_hi v156, v163 offset:464
	ds_write_b64 v127, v[146:147] offset:9216
	ds_write_b64 v127, v[162:163] offset:11520
	v_cvt_pk_bf16_f32 v146, v60, v61
	ds_write_b16 v156, v0 offset:18432
	ds_write_b16_d16_hi v156, v0 offset:18576
	ds_write_b16 v156, v146 offset:18720
	ds_write_b16_d16_hi v156, v146 offset:18864
	v_cvt_pk_bf16_f32 v0, v62, v63
	v_cvt_pk_bf16_f32 v146, v64, v65
	ds_write_b16 v156, v0 offset:18464
	ds_write_b16_d16_hi v156, v0 offset:18608
	ds_write_b16 v156, v146 offset:18752
	ds_write_b16_d16_hi v156, v146 offset:18896
	s_waitcnt lgkmcnt(0)
	s_barrier
	ds_read_b128 v[186:189], v69 offset:18432
	ds_read_b128 v[190:193], v118 offset:9216
	ds_read_b128 v[204:207], v118 offset:11520
	ds_read_b128 v[208:211], v69 offset:18496
	ds_read_b128 v[212:215], v118 offset:9280
	ds_read_b128 v[216:219], v118 offset:11584
	s_nop 0
	s_nop 0
	s_waitcnt lgkmcnt(4)
	v_mfma_f32_16x16x32_bf16 v[58:61], v[186:189], v[190:193], v[58:61]
	s_nop 0
	s_waitcnt lgkmcnt(3)
	v_mfma_f32_16x16x32_bf16 v[62:65], v[186:189], v[204:207], v[62:65]
	s_nop 0
	s_nop 0
	s_waitcnt lgkmcnt(1)
	v_mfma_f32_16x16x32_bf16 v[58:61], v[208:211], v[212:215], v[58:61]
	s_nop 0
	s_waitcnt lgkmcnt(0)
	v_mfma_f32_16x16x32_bf16 v[62:65], v[208:211], v[216:219], v[62:65]
	v_mov_b32_e32 v162, v208
	v_mov_b32_e32 v163, v209
	v_mov_b32_e32 v164, v210
	v_mov_b32_e32 v165, v211
	v_mov_b32_e32 v166, v216
	v_mov_b32_e32 v167, v217
	v_mov_b32_e32 v168, v218
	v_mov_b32_e32 v169, v219
	s_nop 4
	v_cvt_pk_bf16_f32 v0, v58, v59
	v_cvt_pk_bf16_f32 v58, v60, v61
	ds_write_b16 v156, v0 offset:27648
	ds_write_b16_d16_hi v156, v0 offset:27792
	ds_write_b16 v156, v58 offset:27936
	ds_write_b16_d16_hi v156, v58 offset:28080
	v_cvt_pk_bf16_f32 v0, v62, v63
	v_cvt_pk_bf16_f32 v58, v64, v65
	ds_write_b16 v156, v0 offset:27680
	ds_write_b16_d16_hi v156, v0 offset:27824
	ds_write_b16 v156, v58 offset:27968
	ds_write_b16_d16_hi v156, v58 offset:28112
	v_mfma_f32_16x16x32_bf16 v[42:45], v[22:25], v[42:45], 0
	s_waitcnt lgkmcnt(0)
	s_barrier
	v_mfma_f32_16x16x32_bf16 v[58:61], v[22:25], v[46:49], 0
	v_mfma_f32_16x16x32_bf16 v[38:41], v[22:25], v[38:41], 0
	v_mfma_f32_16x16x32_bf16 v[34:37], v[22:25], v[34:37], 0
	v_mfma_f32_16x16x32_bf16 v[46:49], v[18:21], v[54:57], v[42:45]
	v_mfma_f32_16x16x32_bf16 v[42:45], v[18:21], v[50:53], v[58:61]
	v_mfma_f32_16x16x32_bf16 v[22:25], v[18:21], v[30:33], v[38:41]
	v_mfma_f32_16x16x32_bf16 v[18:21], v[18:21], v[26:29], v[34:37]
	s_and_saveexec_b64 s[12:13], vcc
	s_cbranch_execz .LBB0_245
	ds_read_b128 v[26:29], v68 offset:27648
	s_waitcnt lgkmcnt(0)
	global_store_dwordx4 v[100:101], v[26:29], off
; template <bool PA> ...
;     ...
;             mm2(Xacc, MAT(10), MAT(6), mt, ntb, r16, kq);
;             st_tr(MAT(7), Xacc, mt, ntb, r16, kq);
;             if (PA) st_tr(MAT(11), X2acc, mt, ntb, r16, kq);
;             __syncthreads();
;             tmp[0] = z4; tmp[1] = z4; mm2(tmp, Tm, MAT(7), mt, ntb, r16, kq);
;             st_tr(MAT(8), tmp, mt, ntb, r16, kq);
;             if (PA) { tmp[0] = z4; tmp[1] = z4; mm2(tmp, MAT(3), MAT(11), mt, ntb, r16, kq); st_tr(MAT(12), tmp, mt, ntb, r16, kq); }
;             __syncthreads();
;             if (!PA) { mm2(Yacc, MAT(11), MAT(8), mt, ntb, r16, kq); mm2(Yacc, MAT(12), MAT(6), mt, ntb, r16, kq);
;             st_rm(MAT(7), Yacc, mt, ntb, r16, kq); }
;             if (PA) mm2(S2acc, MAT(12), MAT(4), mt, ntb, r16, kq);
;             mm2(Sacc, MAT(8), MAT(4), mt, ntb, r16, kq); mm2(Sacc, MAT(6), MAT(5), mt, ntb, r16, kq);
; #pragma unroll
;             for (int i = 0; i < 2; ++i) { const float wk = wc[16 * (ntb + i) + r16];
; #pragma unroll
;                 for (int e = 0; e < 4; ++e) { Sacc[i][e] *= wk; S2acc[i][e] *= wk; } }
;             __syncthreads();
.LBB0_245:
	s_or_b64 exec, exec, s[12:13]
	ds_read_b128 v[26:29], v128
	ds_read_b128 v[30:33], v118 offset:55296
	s_add_i32 s20, s20, 1
	s_add_i32 s24, s24, -1
	v_lshl_add_u64 v[100:101], v[100:101], 0, s[34:35]
	s_cmp_ge_i32 s20, s21
	s_waitcnt lgkmcnt(0)
	v_mfma_f32_16x16x32_bf16 v[22:25], v[26:29], v[30:33], v[22:25]
	ds_read_b128 v[30:33], v118 offset:57600
	s_waitcnt lgkmcnt(0)
	v_mfma_f32_16x16x32_bf16 v[18:21], v[26:29], v[30:33], v[18:21]
	ds_read_b128 v[26:29], v128 offset:64
	ds_read_b128 v[30:33], v118 offset:55360
	s_waitcnt lgkmcnt(0)
	v_mfma_f32_16x16x32_bf16 v[22:25], v[26:29], v[30:33], v[22:25]
	ds_read_b128 v[30:33], v118 offset:57664
	s_waitcnt lgkmcnt(0)
	v_mfma_f32_16x16x32_bf16 v[18:21], v[26:29], v[30:33], v[18:21]
	s_nop 4
	v_cvt_pk_bf16_f32 v22, v22, v23
	v_cvt_pk_bf16_f32 v23, v24, v25
	ds_write_b64 v127, v[22:23] offset:64512
	v_cvt_pk_bf16_f32 v18, v18, v19
	v_cvt_pk_bf16_f32 v19, v20, v21
	ds_write_b64 v129, v[18:19]
	v_cvt_pk_bf16_f32 v18, v46, v47
	v_cvt_pk_bf16_f32 v19, v48, v49
	ds_write_b64 v130, v[18:19]
	v_cvt_pk_bf16_f32 v18, v42, v43
	v_cvt_pk_bf16_f32 v19, v44, v45
	ds_write_b64 v130, v[18:19] offset:2304
	s_waitcnt lgkmcnt(0)
	s_barrier
	ds_read_b128 v[186:189], v69 offset:27648
	ds_read_b128 v[190:193], v118 offset:64512
	ds_read_b128 v[204:207], v123
	ds_read_b128 v[208:211], v69 offset:27712
	ds_read_b128 v[212:215], v118 offset:64576
	ds_read_b128 v[216:219], v124
	ds_read_b128 v[220:223], v69 offset:27648
	ds_read_b128 v[224:227], v132
	s_nop 0
	s_nop 0
	s_nop 0
	s_waitcnt lgkmcnt(6)
	v_mfma_f32_16x16x32_bf16 v[22:25], v[186:189], v[190:193], 0
	ds_read_b128 v[190:193], v132 offset:2304
	s_waitcnt lgkmcnt(6)
	v_mfma_f32_16x16x32_bf16 v[18:21], v[186:189], v[204:207], 0
	ds_read_b128 v[186:189], v69 offset:27712
	ds_read_b128 v[204:207], v132 offset:64
	s_nop 0
	s_nop 0
	s_waitcnt lgkmcnt(6)
	v_mfma_f32_16x16x32_bf16 v[22:25], v[208:211], v[212:215], v[22:25]
	ds_read_b128 v[212:215], v132 offset:2368
	s_nop 0
	s_waitcnt lgkmcnt(6)
	v_mfma_f32_16x16x32_bf16 v[18:21], v[208:211], v[216:219], v[18:21]
	s_nop 4
	v_cvt_pk_bf16_f32 v22, v22, v23
	v_cvt_pk_bf16_f32 v23, v24, v25
	ds_write_b64 v131, v[22:23]
	v_cvt_pk_bf16_f32 v18, v18, v19
	v_cvt_pk_bf16_f32 v19, v20, v21
	ds_write_b64 v131, v[18:19] offset:2304
	s_nop 0
	s_nop 0
	s_nop 0
	s_waitcnt lgkmcnt(0)
	v_mfma_f32_16x16x32_bf16 v[22:25], v[220:223], v[224:227], 0
	s_waitcnt lgkmcnt(0)
	v_mfma_f32_16x16x32_bf16 v[18:21], v[220:223], v[190:193], 0
	s_nop 0
	s_nop 0
	s_waitcnt lgkmcnt(0)
	v_mfma_f32_16x16x32_bf16 v[22:25], v[186:189], v[204:207], v[22:25]
	s_nop 0
	s_waitcnt lgkmcnt(0)
	v_mfma_f32_16x16x32_bf16 v[18:21], v[186:189], v[212:215], v[18:21]
	s_nop 4
	v_cvt_pk_bf16_f32 v22, v22, v23
	v_cvt_pk_bf16_f32 v23, v24, v25
	ds_write_b64 v133, v[22:23]
	v_cvt_pk_bf16_f32 v18, v18, v19
	v_cvt_pk_bf16_f32 v19, v20, v21
	ds_write_b64 v133, v[18:19] offset:2304
	s_waitcnt lgkmcnt(0)
	s_barrier
	ds_read_b128 v[186:189], v134
	ds_read_b128 v[190:193], v118 offset:36864
	ds_read_b128 v[204:207], v118 offset:39168
	ds_read_b128 v[208:211], v134 offset:64
	ds_read_b128 v[212:215], v118 offset:36928
	ds_read_b128 v[216:219], v118 offset:39232
	ds_read_b128 v[220:223], v125
	ds_read_b128 v[224:227], v125 offset:64
	s_nop 0
	s_nop 0
	s_nop 0
	s_waitcnt lgkmcnt(6)
	v_mfma_f32_16x16x32_bf16 v[10:13], v[186:189], v[190:193], v[10:13]
	s_waitcnt lgkmcnt(5)
	v_mfma_f32_16x16x32_bf16 v[14:17], v[186:189], v[204:207], v[14:17]
	ds_read_b128 v[186:189], v69 offset:55296
	s_nop 0
	s_nop 0
	s_nop 0
	s_waitcnt lgkmcnt(4)
	v_mfma_f32_16x16x32_bf16 v[10:13], v[208:211], v[212:215], v[10:13]
	s_waitcnt lgkmcnt(3)
	v_mfma_f32_16x16x32_bf16 v[14:17], v[208:211], v[216:219], v[14:17]
	ds_read_b128 v[208:211], v118 offset:46080
	s_nop 0
	s_waitcnt lgkmcnt(3)
	v_mfma_f32_16x16x32_bf16 v[2:5], v[220:223], v[190:193], v[2:5]
	ds_read_b128 v[190:193], v118 offset:48384
	v_mfma_f32_16x16x32_bf16 v[6:9], v[220:223], v[204:207], v[6:9]
	v_mov_b32_e32 v26, v204
	v_mov_b32_e32 v27, v205
	v_mov_b32_e32 v28, v206
	v_mov_b32_e32 v29, v207
	ds_read_b128 v[204:207], v69 offset:55360
	ds_read_b128 v[220:223], v118 offset:46144
	s_nop 0
	s_waitcnt lgkmcnt(5)
	v_mfma_f32_16x16x32_bf16 v[2:5], v[224:227], v[212:215], v[2:5]
	v_mov_b32_e32 v30, v212
	v_mov_b32_e32 v31, v213
	v_mov_b32_e32 v32, v214
	v_mov_b32_e32 v33, v215
	ds_read_b128 v[212:215], v118 offset:48448
	v_mfma_f32_16x16x32_bf16 v[6:9], v[224:227], v[216:219], v[6:9]
	v_mov_b32_e32 v34, v216
	v_mov_b32_e32 v35, v217
	v_mov_b32_e32 v36, v218
	v_mov_b32_e32 v37, v219
	s_nop 0
	s_nop 0
	s_waitcnt lgkmcnt(4)
	v_mfma_f32_16x16x32_bf16 v[2:5], v[186:189], v[208:211], v[2:5]
	s_nop 0
	s_waitcnt lgkmcnt(3)
	v_mfma_f32_16x16x32_bf16 v[6:9], v[186:189], v[190:193], v[6:9]
	s_nop 0
	s_nop 0
	ds_read_b32 v0, v157
	s_waitcnt lgkmcnt(0)
	v_pk_mul_f32 v[12:13], v[12:13], v[0:1] op_sel_hi:[1,0]
	v_mfma_f32_16x16x32_bf16 v[2:5], v[204:207], v[220:223], v[2:5]
	s_nop 0
	v_pk_mul_f32 v[10:11], v[10:11], v[0:1] op_sel_hi:[1,0]
	s_waitcnt lgkmcnt(0)
	v_mfma_f32_16x16x32_bf16 v[6:9], v[204:207], v[212:215], v[6:9]
	v_mov_b32_e32 v18, v204
	v_mov_b32_e32 v19, v205
	v_mov_b32_e32 v20, v206
	v_mov_b32_e32 v21, v207
	v_mov_b32_e32 v22, v212
	v_mov_b32_e32 v23, v213
	v_mov_b32_e32 v24, v214
	v_mov_b32_e32 v25, v215
	s_nop 3
	v_mul_f32_e64 v2, v2, v0
	v_mul_f32_e64 v3, v3, v0
	v_pk_mul_f32 v[4:5], v[4:5], v[0:1] op_sel_hi:[1,0]
	ds_read_b32 v0, v158
	s_waitcnt lgkmcnt(0)
	s_barrier
	v_pk_mul_f32 v[6:7], v[6:7], v[0:1] op_sel_hi:[1,0]
	v_pk_mul_f32 v[8:9], v[8:9], v[0:1] op_sel_hi:[1,0]
	v_pk_mul_f32 v[16:17], v[16:17], v[0:1] op_sel_hi:[1,0]
	v_pk_mul_f32 v[14:15], v[14:15], v[0:1] op_sel_hi:[1,0]
	s_cbranch_scc1 .LBB0_193
	v_mov_b32_e32 v0, v9
	s_branch .LBB0_213
